# norm phases: DPP row reductions instead of the 6-hop ds_bpermute wave sums (now that the row loops are pipelined)
# baseline (speedup 1.0000x reference)
.LBB0_167:
	s_waitcnt vmcnt(7)
	v_pk_mul_f32 v[64:65], v[2:3], v[2:3]
	v_pk_mul_f32 v[66:67], v[0:1], v[0:1]
	s_andn2_b64 vcc, exec, s[10:11]
	v_pk_mov_b32 v[68:69], v[66:67], v[64:65] op_sel:[1,0]
	v_mov_b32_e32 v67, v65
	v_pk_add_f32 v[64:65], v[68:69], v[66:67]
	s_waitcnt vmcnt(6)
	v_pk_mul_f32 v[66:67], v[6:7], v[6:7]
	v_pk_add_f32 v[64:65], v[64:65], v[64:65] op_sel_hi:[0,1]
	v_pk_mul_f32 v[68:69], v[4:5], v[4:5]
	s_waitcnt vmcnt(5)
	v_mul_f32_e32 v64, v8, v8
	v_pk_mov_b32 v[80:81], v[68:69], v[66:67] op_sel:[1,0]
	v_mov_b32_e32 v69, v67
	v_pk_add_f32 v[66:67], v[80:81], v[68:69]
	v_pk_fma_f32 v[68:69], v[8:9], v[8:9], v[64:65] op_sel_hi:[1,1,0]
	v_mul_f32_e32 v64, v10, v10
	v_pk_add_f32 v[66:67], v[66:67], v[66:67] op_sel_hi:[0,1]
	v_pk_fma_f32 v[80:81], v[10:11], v[10:11], v[64:65] op_sel_hi:[1,1,0]
	s_waitcnt vmcnt(4)
	v_mul_f32_e32 v68, v12, v12
	v_mul_f32_e32 v80, v13, v13
	v_mul_f32_e32 v64, v14, v14
	v_mul_f32_e32 v66, v15, v15
	v_pk_add_f32 v[68:69], v[68:69], v[80:81]
	v_pk_add_f32 v[64:65], v[64:65], v[66:67]
	v_cndmask_b32_e64 v67, 0, 1, s[10:11]
	v_pk_add_f32 v[64:65], v[68:69], v[64:65]
	v_cmp_ne_u32_e64 s[4:5], 1, v67
	v_add_f32_e32 v64, v64, v65
	s_nop 1
	v_add_f32_dpp v240, v64, v64 quad_perm:[1,0,3,2] row_mask:0xf bank_mask:0xf
	s_nop 1
	v_add_f32_dpp v240, v240, v240 quad_perm:[2,3,0,1] row_mask:0xf bank_mask:0xf
	s_nop 1
	v_add_f32_dpp v240, v240, v240 row_half_mirror row_mask:0xf bank_mask:0xf
	s_nop 1
	v_add_f32_dpp v240, v240, v240 row_mirror row_mask:0xf bank_mask:0xf
	s_nop 1
	v_add_f32_dpp v240, v240, v240 row_bcast:15 row_mask:0xa bank_mask:0xf
	s_nop 1
	v_add_f32_dpp v240, v240, v240 row_bcast:31 row_mask:0xc bank_mask:0xf
	s_nop 0
	v_readlane_b32 s98, v240, 63
	s_nop 1
	v_mov_b32_e32 v67, 1.0
	v_mov_b32_e32 v68, 1.0
	v_mov_b32_e32 v69, 1.0
	s_waitcnt lgkmcnt(0)
	s_waitcnt lgkmcnt(0)
	s_waitcnt lgkmcnt(0)
	s_waitcnt lgkmcnt(0)
	v_mov_b32_e32 v64, 1.0
	s_waitcnt lgkmcnt(0)
	v_mov_b32_e32 v66, 1.0
	s_cbranch_vccnz .LBB0_169
	global_load_dwordx4 v[66:69], v[78:79], off nt
.LBB0_169:
	s_waitcnt lgkmcnt(0)
	v_mov_b32_e32 v65, s98
	v_fmamk_f32 v65, v65, 0x3a800000, v91
	v_rsq_f32_e32 v82, v65
	s_ashr_i32 s17, s16, 31
	s_lshl_b64 s[22:23], s[16:17], 11
	v_lshl_add_u64 v[80:81], v[76:77], 0, s[22:23]
	v_pk_mul_f32 v[92:93], v[0:1], v[82:83] op_sel_hi:[1,0]
	v_pk_mul_f32 v[84:85], v[2:3], v[82:83] op_sel_hi:[1,0]
	s_waitcnt vmcnt(0)
	v_pk_mul_f32 v[66:67], v[92:93], v[66:67]
	v_pk_mul_f32 v[68:69], v[84:85], v[68:69]
	v_cvt_pk_bf16_f32 v66, v66, v67
	s_and_b64 vcc, exec, s[4:5]
	v_cvt_pk_bf16_f32 v67, v68, v69
	global_store_dwordx2 v[80:81], v[66:67], off nt
	v_mov_b32_e32 v65, 1.0
	v_mov_b32_e32 v66, 1.0
	v_mov_b32_e32 v67, 1.0
	s_cbranch_vccnz .LBB0_171
	global_load_dwordx4 v[64:67], v[78:79], off offset:1024 nt

.LBB0_175:
	v_pk_mul_f32 v[68:69], v[18:19], v[18:19]
	v_pk_mul_f32 v[84:85], v[16:17], v[16:17]
	s_and_b64 vcc, exec, s[4:5]
	v_pk_mov_b32 v[92:93], v[84:85], v[68:69] op_sel:[1,0]
	v_mov_b32_e32 v85, v69
	v_pk_add_f32 v[68:69], v[92:93], v[84:85]
	v_pk_mul_f32 v[84:85], v[22:23], v[22:23]
	v_pk_add_f32 v[68:69], v[68:69], v[68:69] op_sel_hi:[0,1]
	v_pk_mul_f32 v[92:93], v[20:21], v[20:21]
	v_mul_f32_e32 v68, v24, v24
	v_pk_mov_b32 v[94:95], v[92:93], v[84:85] op_sel:[1,0]
	v_mov_b32_e32 v93, v85
	v_pk_add_f32 v[84:85], v[94:95], v[92:93]
	v_pk_fma_f32 v[92:93], v[24:25], v[24:25], v[68:69] op_sel_hi:[1,1,0]
	v_mul_f32_e32 v68, v26, v26
	v_pk_add_f32 v[84:85], v[84:85], v[84:85] op_sel_hi:[0,1]
	v_pk_fma_f32 v[94:95], v[26:27], v[26:27], v[68:69] op_sel_hi:[1,1,0]
	v_mul_f32_e32 v92, v28, v28
	v_mul_f32_e32 v94, v29, v29
	v_mul_f32_e32 v68, v30, v30
	v_mul_f32_e32 v84, v31, v31
	v_pk_add_f32 v[92:93], v[92:93], v[94:95]
	v_pk_add_f32 v[68:69], v[68:69], v[84:85]
	s_nop 0
	v_pk_add_f32 v[68:69], v[92:93], v[68:69]
	s_nop 0
	v_add_f32_e32 v68, v68, v69
	s_nop 1
	v_add_f32_dpp v240, v68, v68 quad_perm:[1,0,3,2] row_mask:0xf bank_mask:0xf
	s_nop 1
	v_add_f32_dpp v240, v240, v240 quad_perm:[2,3,0,1] row_mask:0xf bank_mask:0xf
	s_nop 1
	v_add_f32_dpp v240, v240, v240 row_half_mirror row_mask:0xf bank_mask:0xf
	s_nop 1
	v_add_f32_dpp v240, v240, v240 row_mirror row_mask:0xf bank_mask:0xf
	s_nop 1
	v_add_f32_dpp v240, v240, v240 row_bcast:15 row_mask:0xa bank_mask:0xf
	s_nop 1
	v_add_f32_dpp v240, v240, v240 row_bcast:31 row_mask:0xc bank_mask:0xf
	s_nop 0
	v_readlane_b32 s98, v240, 63
	s_nop 1
	s_waitcnt lgkmcnt(0)
	s_waitcnt lgkmcnt(0)
	v_mov_b32_e32 v68, v82
	s_waitcnt lgkmcnt(0)
	v_mov_b32_e32 v69, v82
	v_pk_mul_f32 v[68:69], v[14:15], v[68:69]
	v_pk_mul_f32 v[82:83], v[12:13], v[82:83]
	s_waitcnt vmcnt(0)
	v_pk_mul_f32 v[66:67], v[68:69], v[66:67]
	s_waitcnt lgkmcnt(0)
	v_pk_mul_f32 v[64:65], v[82:83], v[64:65]
	s_nop 0
	v_cvt_pk_bf16_f32 v64, v64, v65
	v_cvt_pk_bf16_f32 v65, v66, v67
	global_store_dwordx2 v[80:81], v[64:65], off offset:1536 nt
	s_waitcnt lgkmcnt(0)
	v_mov_b32_e32 v64, 1.0
	v_mov_b32_e32 v66, 1.0
	v_mov_b32_e32 v67, 1.0
	v_mov_b32_e32 v68, 1.0
	v_mov_b32_e32 v69, 1.0
	s_cbranch_vccnz .LBB0_177
	global_load_dwordx4 v[66:69], v[78:79], off nt
.LBB0_177:
	s_waitcnt lgkmcnt(0)
	v_mov_b32_e32 v65, s98
	v_fmamk_f32 v65, v65, 0x3a800000, v91
	v_rsq_f32_e32 v82, v65
	s_ashr_i32 s9, s8, 31
	s_lshl_b64 s[22:23], s[8:9], 11
	v_lshl_add_u64 v[80:81], v[76:77], 0, s[22:23]
	v_pk_mul_f32 v[92:93], v[16:17], v[82:83] op_sel_hi:[1,0]
	v_pk_mul_f32 v[84:85], v[18:19], v[82:83] op_sel_hi:[1,0]
	s_waitcnt vmcnt(0)
	v_pk_mul_f32 v[66:67], v[92:93], v[66:67]
	v_pk_mul_f32 v[68:69], v[84:85], v[68:69]
	v_cvt_pk_bf16_f32 v66, v66, v67
	s_and_b64 vcc, exec, s[4:5]
	v_cvt_pk_bf16_f32 v67, v68, v69
	global_store_dwordx2 v[80:81], v[66:67], off nt
	v_mov_b32_e32 v65, 1.0
	v_mov_b32_e32 v66, 1.0
	v_mov_b32_e32 v67, 1.0
	s_cbranch_vccnz .LBB0_179
	global_load_dwordx4 v[64:67], v[78:79], off offset:1024 nt

.LBB0_186:
	v_pk_mul_f32 v[64:65], v[34:35], v[34:35]
	v_pk_mul_f32 v[66:67], v[32:33], v[32:33]
	s_and_b64 vcc, exec, s[4:5]
	v_pk_mov_b32 v[68:69], v[66:67], v[64:65] op_sel:[1,0]
	v_mov_b32_e32 v67, v65
	v_pk_add_f32 v[64:65], v[68:69], v[66:67]
	v_pk_mul_f32 v[66:67], v[38:39], v[38:39]
	v_pk_add_f32 v[64:65], v[64:65], v[64:65] op_sel_hi:[0,1]
	v_pk_mul_f32 v[68:69], v[36:37], v[36:37]
	v_mul_f32_e32 v64, v40, v40
	v_pk_mov_b32 v[80:81], v[68:69], v[66:67] op_sel:[1,0]
	v_mov_b32_e32 v69, v67
	v_pk_add_f32 v[66:67], v[80:81], v[68:69]
	v_pk_fma_f32 v[68:69], v[40:41], v[40:41], v[64:65] op_sel_hi:[1,1,0]
	v_mul_f32_e32 v64, v42, v42
	v_pk_add_f32 v[66:67], v[66:67], v[66:67] op_sel_hi:[0,1]
	v_pk_fma_f32 v[80:81], v[42:43], v[42:43], v[64:65] op_sel_hi:[1,1,0]
	v_mul_f32_e32 v68, v44, v44
	v_mul_f32_e32 v80, v45, v45
	v_mul_f32_e32 v66, v46, v46
	v_mul_f32_e32 v64, v47, v47
	v_pk_add_f32 v[68:69], v[68:69], v[80:81]
	v_pk_add_f32 v[64:65], v[66:67], v[64:65]
	v_mov_b32_e32 v67, 1.0
	v_pk_add_f32 v[64:65], v[68:69], v[64:65]
	v_mov_b32_e32 v68, 1.0
	v_add_f32_e32 v64, v64, v65
	s_nop 1
	v_add_f32_dpp v240, v64, v64 quad_perm:[1,0,3,2] row_mask:0xf bank_mask:0xf
	s_nop 1
	v_add_f32_dpp v240, v240, v240 quad_perm:[2,3,0,1] row_mask:0xf bank_mask:0xf
	s_nop 1
	v_add_f32_dpp v240, v240, v240 row_half_mirror row_mask:0xf bank_mask:0xf
	s_nop 1
	v_add_f32_dpp v240, v240, v240 row_mirror row_mask:0xf bank_mask:0xf
	s_nop 1
	v_add_f32_dpp v240, v240, v240 row_bcast:15 row_mask:0xa bank_mask:0xf
	s_nop 1
	v_add_f32_dpp v240, v240, v240 row_bcast:31 row_mask:0xc bank_mask:0xf
	s_nop 0
	v_readlane_b32 s98, v240, 63
	s_nop 1
	v_mov_b32_e32 v69, 1.0
	s_waitcnt lgkmcnt(0)
	s_waitcnt lgkmcnt(0)
	s_waitcnt lgkmcnt(0)
	s_waitcnt lgkmcnt(0)
	v_mov_b32_e32 v64, 1.0
	s_waitcnt lgkmcnt(0)
	v_mov_b32_e32 v66, 1.0
	s_cbranch_vccnz .LBB0_188
	global_load_dwordx4 v[66:69], v[78:79], off nt
.LBB0_188:
	s_waitcnt lgkmcnt(0)
	v_mov_b32_e32 v65, s98
	v_fmamk_f32 v65, v65, 0x3a800000, v91
	v_rsq_f32_e32 v82, v65
	s_ashr_i32 s15, s14, 31
	s_lshl_b64 s[20:21], s[14:15], 11
	v_lshl_add_u64 v[80:81], v[76:77], 0, s[20:21]
	v_pk_mul_f32 v[92:93], v[32:33], v[82:83] op_sel_hi:[1,0]
	v_pk_mul_f32 v[84:85], v[34:35], v[82:83] op_sel_hi:[1,0]
	s_waitcnt vmcnt(0)
	v_pk_mul_f32 v[66:67], v[92:93], v[66:67]
	v_pk_mul_f32 v[68:69], v[84:85], v[68:69]
	v_cvt_pk_bf16_f32 v66, v66, v67
	s_and_b64 vcc, exec, s[4:5]
	v_cvt_pk_bf16_f32 v67, v68, v69
	global_store_dwordx2 v[80:81], v[66:67], off nt
	v_mov_b32_e32 v65, 1.0
	v_mov_b32_e32 v66, 1.0
	v_mov_b32_e32 v67, 1.0
	s_cbranch_vccnz .LBB0_190
	global_load_dwordx4 v[64:67], v[78:79], off offset:1024 nt

.LBB0_194:
	v_pk_mul_f32 v[68:69], v[50:51], v[50:51]
	v_pk_mul_f32 v[84:85], v[48:49], v[48:49]
	s_and_b64 vcc, exec, s[4:5]
	v_pk_mov_b32 v[92:93], v[84:85], v[68:69] op_sel:[1,0]
	v_mov_b32_e32 v85, v69
	v_pk_add_f32 v[68:69], v[92:93], v[84:85]
	v_pk_mul_f32 v[84:85], v[54:55], v[54:55]
	v_pk_add_f32 v[68:69], v[68:69], v[68:69] op_sel_hi:[0,1]
	v_pk_mul_f32 v[92:93], v[52:53], v[52:53]
	v_mul_f32_e32 v68, v56, v56
	v_pk_mov_b32 v[94:95], v[92:93], v[84:85] op_sel:[1,0]
	v_mov_b32_e32 v93, v85
	v_pk_add_f32 v[84:85], v[94:95], v[92:93]
	v_pk_fma_f32 v[92:93], v[56:57], v[56:57], v[68:69] op_sel_hi:[1,1,0]
	v_mul_f32_e32 v68, v58, v58
	v_pk_add_f32 v[84:85], v[84:85], v[84:85] op_sel_hi:[0,1]
	v_pk_fma_f32 v[94:95], v[58:59], v[58:59], v[68:69] op_sel_hi:[1,1,0]
	v_mul_f32_e32 v92, v60, v60
	v_mul_f32_e32 v94, v61, v61
	v_mul_f32_e32 v84, v62, v62
	v_mul_f32_e32 v68, v63, v63
	v_pk_add_f32 v[92:93], v[92:93], v[94:95]
	v_pk_add_f32 v[68:69], v[84:85], v[68:69]
	s_nop 0
	v_pk_add_f32 v[68:69], v[92:93], v[68:69]
	s_nop 0
	v_add_f32_e32 v68, v68, v69
	s_nop 1
	v_add_f32_dpp v240, v68, v68 quad_perm:[1,0,3,2] row_mask:0xf bank_mask:0xf
	s_nop 1
	v_add_f32_dpp v240, v240, v240 quad_perm:[2,3,0,1] row_mask:0xf bank_mask:0xf
	s_nop 1
	v_add_f32_dpp v240, v240, v240 row_half_mirror row_mask:0xf bank_mask:0xf
	s_nop 1
	v_add_f32_dpp v240, v240, v240 row_mirror row_mask:0xf bank_mask:0xf
	s_nop 1
	v_add_f32_dpp v240, v240, v240 row_bcast:15 row_mask:0xa bank_mask:0xf
	s_nop 1
	v_add_f32_dpp v240, v240, v240 row_bcast:31 row_mask:0xc bank_mask:0xf
	s_nop 0
	v_readlane_b32 s98, v240, 63
	s_nop 1
	s_waitcnt lgkmcnt(0)
	s_waitcnt lgkmcnt(0)
	v_mov_b32_e32 v68, v82
	s_waitcnt lgkmcnt(0)
	v_mov_b32_e32 v69, v82
	v_pk_mul_f32 v[68:69], v[46:47], v[68:69]
	v_pk_mul_f32 v[82:83], v[44:45], v[82:83]
	s_waitcnt vmcnt(0)
	v_pk_mul_f32 v[66:67], v[68:69], v[66:67]
	s_waitcnt lgkmcnt(0)
	v_pk_mul_f32 v[64:65], v[82:83], v[64:65]
	s_nop 0
	v_cvt_pk_bf16_f32 v64, v64, v65
	v_cvt_pk_bf16_f32 v65, v66, v67
	global_store_dwordx2 v[80:81], v[64:65], off offset:1536 nt
	s_waitcnt lgkmcnt(0)
	v_mov_b32_e32 v64, 1.0
	v_mov_b32_e32 v66, 1.0
	v_mov_b32_e32 v67, 1.0
	v_mov_b32_e32 v68, 1.0
	v_mov_b32_e32 v69, 1.0
	s_cbranch_vccnz .LBB0_196
	global_load_dwordx4 v[66:69], v[78:79], off nt
.LBB0_196:
	s_waitcnt lgkmcnt(0)
	v_mov_b32_e32 v65, s98
	v_fmamk_f32 v65, v65, 0x3a800000, v91
	v_rsq_f32_e32 v82, v65
	s_ashr_i32 s13, s12, 31
	s_lshl_b64 s[20:21], s[12:13], 11
	v_lshl_add_u64 v[80:81], v[76:77], 0, s[20:21]
	v_pk_mul_f32 v[92:93], v[48:49], v[82:83] op_sel_hi:[1,0]
	v_pk_mul_f32 v[84:85], v[50:51], v[82:83] op_sel_hi:[1,0]
	s_waitcnt vmcnt(0)
	v_pk_mul_f32 v[66:67], v[92:93], v[66:67]
	v_pk_mul_f32 v[68:69], v[84:85], v[68:69]
	v_cvt_pk_bf16_f32 v66, v66, v67
	s_and_b64 vcc, exec, s[4:5]
	v_cvt_pk_bf16_f32 v67, v68, v69
	global_store_dwordx2 v[80:81], v[66:67], off nt
	v_mov_b32_e32 v65, 1.0
	v_mov_b32_e32 v66, 1.0
	v_mov_b32_e32 v67, 1.0
	s_cbranch_vccnz .LBB0_198
	global_load_dwordx4 v[64:67], v[78:79], off offset:1024 nt

.LBB0_208:
	v_mul_f32_e32 v70, v1, v1
	s_waitcnt lgkmcnt(0)
	v_mul_f32_e32 v71, v3, v3
	v_fmac_f32_e32 v70, v0, v0
	v_fmac_f32_e32 v71, v2, v2
	v_add_f32_e32 v70, v70, v71
	v_mul_f32_e32 v71, v5, v5
	v_mul_f32_e32 v72, v7, v7
	v_fmac_f32_e32 v71, v4, v4
	v_fmac_f32_e32 v72, v6, v6
	v_add_f32_e32 v71, v71, v72
	v_add_f32_e32 v70, v70, v71
	v_mul_f32_e32 v71, v9, v9
	v_mul_f32_e32 v72, v11, v11
	v_fmac_f32_e32 v71, v8, v8
	v_fmac_f32_e32 v72, v10, v10
	v_add_f32_e32 v71, v71, v72
	v_add_f32_e32 v70, v71, v70
	v_mul_f32_e32 v71, v13, v13
	v_mul_f32_e32 v72, v15, v15
	v_fmac_f32_e32 v71, v12, v12
	v_fmac_f32_e32 v72, v14, v14
	v_add_f32_e32 v71, v71, v72
	v_add_f32_e32 v71, v71, v70
	v_and_b32_e32 v70, 64, v68
	v_add_u32_e32 v78, 64, v70
	v_xor_b32_e32 v70, 1, v68
	v_cmp_lt_i32_e32 vcc, v70, v78
	s_ashr_i32 s15, s14, 31
	s_lshl_b64 s[20:21], s[14:15], 11
	v_cndmask_b32_e32 v70, v68, v70, vcc
	v_lshlrev_b32_e32 v70, 2, v70
	s_nop 1
	v_add_f32_dpp v240, v71, v71 quad_perm:[1,0,3,2] row_mask:0xf bank_mask:0xf
	s_nop 1
	v_add_f32_dpp v240, v240, v240 quad_perm:[2,3,0,1] row_mask:0xf bank_mask:0xf
	s_nop 1
	v_add_f32_dpp v240, v240, v240 row_half_mirror row_mask:0xf bank_mask:0xf
	s_nop 1
	v_add_f32_dpp v240, v240, v240 row_mirror row_mask:0xf bank_mask:0xf
	s_nop 1
	v_add_f32_dpp v240, v240, v240 row_bcast:15 row_mask:0xa bank_mask:0xf
	s_nop 1
	v_add_f32_dpp v240, v240, v240 row_bcast:31 row_mask:0xc bank_mask:0xf
	s_nop 0
	v_readlane_b32 s98, v240, 63
	s_nop 1
	v_lshl_add_u64 v[80:81], v[66:67], 0, s[20:21]
	v_cvt_pk_bf16_f32 v76, v0, v1
	v_cvt_pk_bf16_f32 v77, v2, v3
	global_store_dwordx2 v[80:81], v[76:77], off nt
	s_waitcnt lgkmcnt(0)
	v_xor_b32_e32 v71, 2, v68
	v_cmp_lt_i32_e32 vcc, v71, v78
	v_cvt_pk_bf16_f32 v76, v4, v5
	v_cvt_pk_bf16_f32 v77, v6, v7
	global_store_dwordx2 v[80:81], v[76:77], off offset:512 nt
	v_xor_b32_e32 v76, 32, v68
	v_cndmask_b32_e32 v71, v68, v71, vcc
	v_lshlrev_b32_e32 v71, 2, v71
	v_cvt_pk_bf16_f32 v82, v8, v9
	v_cvt_pk_bf16_f32 v83, v10, v11
	global_store_dwordx2 v[80:81], v[82:83], off offset:1024 nt
	v_cvt_pk_bf16_f32 v82, v12, v13
	s_waitcnt lgkmcnt(0)
	v_xor_b32_e32 v72, 4, v68
	v_cmp_lt_i32_e32 vcc, v72, v78
	v_cvt_pk_bf16_f32 v83, v14, v15
	global_store_dwordx2 v[80:81], v[82:83], off offset:1536 nt
	s_nop 0
	v_cndmask_b32_e32 v72, v68, v72, vcc
	v_lshlrev_b32_e32 v72, 2, v72
	s_waitcnt lgkmcnt(0)
	v_xor_b32_e32 v74, 8, v68
	v_cmp_lt_i32_e32 vcc, v74, v78
	s_nop 1
	v_cndmask_b32_e32 v74, v68, v74, vcc
	v_lshlrev_b32_e32 v74, 2, v74
	s_waitcnt lgkmcnt(0)
	v_xor_b32_e32 v75, 16, v68
	v_cmp_lt_i32_e32 vcc, v75, v78
	s_nop 1
	v_cndmask_b32_e32 v75, v68, v75, vcc
	v_lshlrev_b32_e32 v75, 2, v75
	v_cmp_lt_i32_e32 vcc, v76, v78
	s_waitcnt lgkmcnt(0)
	s_nop 0
	v_cndmask_b32_e32 v76, v68, v76, vcc
	v_lshlrev_b32_e32 v76, 2, v76
	s_and_saveexec_b64 s[20:21], s[4:5]
	s_cbranch_execz .LBB0_210
	s_waitcnt lgkmcnt(0)
	v_mov_b32_e32 v77, s98
	v_fmamk_f32 v77, v77, 0x3a800000, v69
	v_rsq_f32_e32 v77, v77
	s_lshl_b64 s[28:29], s[14:15], 2
	s_add_u32 s28, s22, s28
	s_addc_u32 s29, s23, s29
	global_store_dword v73, v77, s[28:29]
.LBB0_210:
	s_or_b64 exec, exec, s[20:21]
	v_mul_f32_e32 v77, v17, v17
	s_waitcnt lgkmcnt(0)
	v_mul_f32_e32 v78, v19, v19
	v_fmac_f32_e32 v77, v16, v16
	v_fmac_f32_e32 v78, v18, v18
	v_add_f32_e32 v77, v77, v78
	v_mul_f32_e32 v78, v21, v21
	v_mul_f32_e32 v79, v23, v23
	v_fmac_f32_e32 v78, v20, v20
	v_fmac_f32_e32 v79, v22, v22
	v_add_f32_e32 v78, v78, v79
	v_add_f32_e32 v77, v77, v78
	v_mul_f32_e32 v78, v25, v25
	v_mul_f32_e32 v79, v27, v27
	v_fmac_f32_e32 v78, v24, v24
	v_fmac_f32_e32 v79, v26, v26
	v_add_f32_e32 v78, v78, v79
	v_add_f32_e32 v77, v78, v77
	v_mul_f32_e32 v78, v29, v29
	v_mul_f32_e32 v79, v31, v31
	v_fmac_f32_e32 v78, v28, v28
	v_fmac_f32_e32 v79, v30, v30
	v_add_f32_e32 v78, v78, v79
	v_add_f32_e32 v77, v78, v77
	s_nop 1
	v_add_f32_dpp v240, v77, v77 quad_perm:[1,0,3,2] row_mask:0xf bank_mask:0xf
	s_nop 1
	v_add_f32_dpp v240, v240, v240 quad_perm:[2,3,0,1] row_mask:0xf bank_mask:0xf
	s_nop 1
	v_add_f32_dpp v240, v240, v240 row_half_mirror row_mask:0xf bank_mask:0xf
	s_nop 1
	v_add_f32_dpp v240, v240, v240 row_mirror row_mask:0xf bank_mask:0xf
	s_nop 1
	v_add_f32_dpp v240, v240, v240 row_bcast:15 row_mask:0xa bank_mask:0xf
	s_nop 1
	v_add_f32_dpp v240, v240, v240 row_bcast:31 row_mask:0xc bank_mask:0xf
	s_nop 0
	v_readlane_b32 s98, v240, 63
	s_nop 1
	s_ashr_i32 s9, s8, 31
	s_lshl_b64 s[20:21], s[8:9], 11
	v_lshl_add_u64 v[80:81], v[66:67], 0, s[20:21]
	s_waitcnt lgkmcnt(0)
	s_waitcnt lgkmcnt(0)
	s_waitcnt lgkmcnt(0)
	v_cvt_pk_bf16_f32 v78, v16, v17
	v_cvt_pk_bf16_f32 v79, v18, v19
	global_store_dwordx2 v[80:81], v[78:79], off nt
	v_cvt_pk_bf16_f32 v78, v20, v21
	s_waitcnt lgkmcnt(0)
	v_cvt_pk_bf16_f32 v79, v22, v23
	global_store_dwordx2 v[80:81], v[78:79], off offset:512 nt
	v_cvt_pk_bf16_f32 v82, v24, v25
	v_cvt_pk_bf16_f32 v83, v26, v27
	s_waitcnt lgkmcnt(0)
	global_store_dwordx2 v[80:81], v[82:83], off offset:1024 nt
	v_cvt_pk_bf16_f32 v82, v28, v29
	v_cvt_pk_bf16_f32 v83, v30, v31
	global_store_dwordx2 v[80:81], v[82:83], off offset:1536 nt
	s_and_saveexec_b64 s[20:21], s[4:5]
	s_cbranch_execnz .LBB0_213
	s_or_b64 exec, exec, s[20:21]
	s_waitcnt vmcnt(9)
	s_add_i32 s20, s24, s6
	s_cmpk_gt_i32 s20, 0x7fff
	s_cbranch_scc0 .LBB0_214

.LBB0_213:
	s_waitcnt lgkmcnt(0)
	v_mov_b32_e32 v77, s98
	v_fmamk_f32 v77, v77, 0x3a800000, v69
	v_rsq_f32_e32 v77, v77
	s_lshl_b64 s[28:29], s[8:9], 2
	s_add_u32 s28, s22, s28
	s_addc_u32 s29, s23, s29
	global_store_dword v73, v77, s[28:29]
	s_waitcnt vmcnt(10)
	s_or_b64 exec, exec, s[20:21]
	s_add_i32 s20, s24, s6
	s_cmpk_gt_i32 s20, 0x7fff
	s_cbranch_scc1 .LBB0_212

.LBB0_215:
	v_mul_f32_e32 v77, v33, v33
	s_waitcnt lgkmcnt(0)
	v_mul_f32_e32 v78, v35, v35
	v_fmac_f32_e32 v77, v32, v32
	v_fmac_f32_e32 v78, v34, v34
	v_add_f32_e32 v77, v77, v78
	v_mul_f32_e32 v78, v37, v37
	v_mul_f32_e32 v79, v39, v39
	v_fmac_f32_e32 v78, v36, v36
	v_fmac_f32_e32 v79, v38, v38
	v_add_f32_e32 v78, v78, v79
	v_add_f32_e32 v77, v78, v77
	v_mul_f32_e32 v78, v41, v41
	v_mul_f32_e32 v79, v43, v43
	v_fmac_f32_e32 v78, v40, v40
	v_fmac_f32_e32 v79, v42, v42
	v_add_f32_e32 v78, v78, v79
	v_add_f32_e32 v77, v78, v77
	v_mul_f32_e32 v78, v45, v45
	v_mul_f32_e32 v79, v47, v47
	v_fmac_f32_e32 v78, v44, v44
	v_fmac_f32_e32 v79, v46, v46
	v_add_f32_e32 v78, v78, v79
	v_add_f32_e32 v77, v78, v77
	s_nop 1
	v_add_f32_dpp v240, v77, v77 quad_perm:[1,0,3,2] row_mask:0xf bank_mask:0xf
	s_nop 1
	v_add_f32_dpp v240, v240, v240 quad_perm:[2,3,0,1] row_mask:0xf bank_mask:0xf
	s_nop 1
	v_add_f32_dpp v240, v240, v240 row_half_mirror row_mask:0xf bank_mask:0xf
	s_nop 1
	v_add_f32_dpp v240, v240, v240 row_mirror row_mask:0xf bank_mask:0xf
	s_nop 1
	v_add_f32_dpp v240, v240, v240 row_bcast:15 row_mask:0xa bank_mask:0xf
	s_nop 1
	v_add_f32_dpp v240, v240, v240 row_bcast:31 row_mask:0xc bank_mask:0xf
	s_nop 0
	v_readlane_b32 s98, v240, 63
	s_nop 1
	s_ashr_i32 s13, s12, 31
	s_lshl_b64 s[6:7], s[12:13], 11
	v_lshl_add_u64 v[80:81], v[66:67], 0, s[6:7]
	s_waitcnt lgkmcnt(0)
	s_waitcnt lgkmcnt(0)
	s_waitcnt lgkmcnt(0)
	v_cvt_pk_bf16_f32 v78, v32, v33
	v_cvt_pk_bf16_f32 v79, v34, v35
	global_store_dwordx2 v[80:81], v[78:79], off nt
	v_cvt_pk_bf16_f32 v78, v36, v37
	s_waitcnt lgkmcnt(0)
	v_cvt_pk_bf16_f32 v79, v38, v39
	global_store_dwordx2 v[80:81], v[78:79], off offset:512 nt
	v_cvt_pk_bf16_f32 v82, v40, v41
	v_cvt_pk_bf16_f32 v83, v42, v43
	s_waitcnt lgkmcnt(0)
	global_store_dwordx2 v[80:81], v[82:83], off offset:1024 nt
	v_cvt_pk_bf16_f32 v82, v44, v45
	v_cvt_pk_bf16_f32 v83, v46, v47
	global_store_dwordx2 v[80:81], v[82:83], off offset:1536 nt
	s_and_saveexec_b64 s[6:7], s[4:5]
	s_cbranch_execz .LBB0_217
	s_waitcnt lgkmcnt(0)
	v_mov_b32_e32 v77, s98
	v_fmamk_f32 v77, v77, 0x3a800000, v69
	v_rsq_f32_e32 v77, v77
	s_lshl_b64 s[18:19], s[12:13], 2
	s_add_u32 s18, s22, s18
	s_addc_u32 s19, s23, s19
	global_store_dword v73, v77, s[18:19]
.LBB0_217:
	s_or_b64 exec, exec, s[6:7]
	v_mul_f32_e32 v77, v49, v49
	s_waitcnt lgkmcnt(0)
	v_mul_f32_e32 v78, v51, v51
	v_fmac_f32_e32 v77, v48, v48
	v_fmac_f32_e32 v78, v50, v50
	v_add_f32_e32 v77, v77, v78
	v_mul_f32_e32 v78, v53, v53
	v_mul_f32_e32 v79, v55, v55
	v_fmac_f32_e32 v78, v52, v52
	v_fmac_f32_e32 v79, v54, v54
	v_add_f32_e32 v78, v78, v79
	v_add_f32_e32 v77, v78, v77
	v_mul_f32_e32 v78, v57, v57
	v_mul_f32_e32 v79, v59, v59
	v_fmac_f32_e32 v78, v56, v56
	v_fmac_f32_e32 v79, v58, v58
	v_add_f32_e32 v78, v78, v79
	v_add_f32_e32 v77, v78, v77
	v_mul_f32_e32 v78, v61, v61
	v_mul_f32_e32 v79, v63, v63
	v_fmac_f32_e32 v78, v60, v60
	v_fmac_f32_e32 v79, v62, v62
	v_add_f32_e32 v78, v78, v79
	v_add_f32_e32 v77, v78, v77
	s_nop 1
	v_add_f32_dpp v240, v77, v77 quad_perm:[1,0,3,2] row_mask:0xf bank_mask:0xf
	s_nop 1
	v_add_f32_dpp v240, v240, v240 quad_perm:[2,3,0,1] row_mask:0xf bank_mask:0xf
	s_nop 1
	v_add_f32_dpp v240, v240, v240 row_half_mirror row_mask:0xf bank_mask:0xf
	s_nop 1
	v_add_f32_dpp v240, v240, v240 row_mirror row_mask:0xf bank_mask:0xf
	s_nop 1
	v_add_f32_dpp v240, v240, v240 row_bcast:15 row_mask:0xa bank_mask:0xf
	s_nop 1
	v_add_f32_dpp v240, v240, v240 row_bcast:31 row_mask:0xc bank_mask:0xf
	s_nop 0
	v_readlane_b32 s98, v240, 63
	s_nop 1
	s_ashr_i32 s11, s10, 31
	s_lshl_b64 s[6:7], s[10:11], 11
	v_lshl_add_u64 v[78:79], v[66:67], 0, s[6:7]
	s_waitcnt lgkmcnt(0)
	s_waitcnt lgkmcnt(0)
	s_waitcnt lgkmcnt(0)
	v_cvt_pk_bf16_f32 v70, v48, v49
	v_cvt_pk_bf16_f32 v71, v50, v51
	global_store_dwordx2 v[78:79], v[70:71], off nt
	v_cvt_pk_bf16_f32 v70, v52, v53
	s_waitcnt lgkmcnt(0)
	v_cvt_pk_bf16_f32 v71, v54, v55
	global_store_dwordx2 v[78:79], v[70:71], off offset:512 nt
	v_cvt_pk_bf16_f32 v74, v56, v57
	v_cvt_pk_bf16_f32 v75, v58, v59
	s_waitcnt lgkmcnt(0)
	global_store_dwordx2 v[78:79], v[74:75], off offset:1024 nt
	v_cvt_pk_bf16_f32 v74, v60, v61
	v_cvt_pk_bf16_f32 v75, v62, v63
	global_store_dwordx2 v[78:79], v[74:75], off offset:1536 nt
	s_and_saveexec_b64 s[6:7], s[4:5]
	s_cbranch_execz .LBB0_204
	s_waitcnt lgkmcnt(0)
	v_mov_b32_e32 v70, s98
	v_fmamk_f32 v70, v70, 0x3a800000, v69
	v_rsq_f32_e32 v70, v70
	s_lshl_b64 s[18:19], s[10:11], 2
	s_add_u32 s18, s22, s18
	s_addc_u32 s19, s23, s19
	global_store_dword v73, v70, s[18:19]
	s_branch .LBB0_204

.LBB0_705:
	v_and_b32_e32 v99, 0xffff0000, v33
	v_and_b32_e32 v98, 0xffff0000, v32
	v_lshlrev_b32_e32 v97, 16, v33
	v_lshlrev_b32_e32 v96, 16, v32
	v_pk_mul_f32 v[84:85], v[98:99], v[98:99]
	s_waitcnt lgkmcnt(0)
	v_pk_fma_f32 v[84:85], v[96:97], v[96:97], v[84:85]
	v_and_b32_e32 v105, 0xffff0000, v35
	v_and_b32_e32 v104, 0xffff0000, v34
	v_pk_add_f32 v[100:101], v[84:85], v[84:85] op_sel_hi:[0,1]
	v_lshlrev_b32_e32 v103, 16, v35
	v_lshlrev_b32_e32 v102, 16, v34
	v_pk_mul_f32 v[92:93], v[104:105], v[104:105]
	v_pk_fma_f32 v[92:93], v[102:103], v[102:103], v[92:93]
	v_lshlrev_b32_e32 v108, 16, v36
	v_pk_add_f32 v[106:107], v[92:93], v[92:93] op_sel_hi:[0,1]
	v_and_b32_e32 v109, 0xffff0000, v36
	v_lshlrev_b32_e32 v114, 16, v37
	v_lshlrev_b32_e32 v110, 16, v38
	v_mul_f32_e32 v111, v108, v108
	v_mul_f32_e32 v113, v109, v109
	v_and_b32_e32 v115, 0xffff0000, v37
	v_mul_f32_e32 v100, v114, v114
	v_mov_b32_e32 v112, v110
	v_pk_fma_f32 v[116:117], v[114:115], v[114:115], v[100:101] op_sel_hi:[1,1,0]
	v_and_b32_e32 v132, 0xffff0000, v38
	v_lshlrev_b32_e32 v118, 16, v39
	v_and_b32_e32 v119, 0xffff0000, v39
	v_pk_add_f32 v[112:113], v[110:111], v[112:113]
	v_mul_f32_e32 v116, v132, v132
	v_mul_f32_e32 v100, v118, v118
	v_mul_f32_e32 v106, v119, v119
	v_mul_f32_e32 v120, v110, v110
	v_mov_b32_e32 v121, v113
	v_pk_add_f32 v[112:113], v[120:121], v[116:117]
	v_pk_add_f32 v[100:101], v[100:101], v[106:107]
	v_mov_b32_e32 v128, v96
	v_pk_add_f32 v[100:101], v[112:113], v[100:101]
	v_mov_b32_e32 v129, v98
	v_add_f32_e32 v100, v100, v101
	s_nop 1
	v_add_f32_dpp v240, v100, v100 quad_perm:[1,0,3,2] row_mask:0xf bank_mask:0xf
	s_nop 1
	v_add_f32_dpp v240, v240, v240 quad_perm:[2,3,0,1] row_mask:0xf bank_mask:0xf
	s_nop 1
	v_add_f32_dpp v240, v240, v240 row_half_mirror row_mask:0xf bank_mask:0xf
	s_nop 1
	v_add_f32_dpp v240, v240, v240 row_mirror row_mask:0xf bank_mask:0xf
	s_nop 1
	v_add_f32_dpp v240, v240, v240 row_bcast:15 row_mask:0xa bank_mask:0xf
	s_nop 1
	v_add_f32_dpp v240, v240, v240 row_bcast:31 row_mask:0xc bank_mask:0xf
	s_nop 0
	v_readlane_b32 s98, v240, 63
	s_nop 1
	v_mov_b32_e32 v98, v97
	v_mov_b32_e32 v131, v104
	v_mov_b32_e32 v104, v103
	v_and_b32_e32 v117, 0xffff0000, v27
	s_waitcnt lgkmcnt(0)
	v_lshlrev_b32_e32 v100, 16, v24
	v_and_b32_e32 v101, 0xffff0000, v24
	v_lshlrev_b32_e32 v120, 16, v28
	v_and_b32_e32 v121, 0xffff0000, v28
	s_waitcnt lgkmcnt(0)
	v_lshlrev_b32_e32 v106, 16, v25
	v_and_b32_e32 v107, 0xffff0000, v25
	v_and_b32_e32 v127, 0xffff0000, v31
	v_lshlrev_b32_e32 v112, 16, v26
	s_waitcnt lgkmcnt(0)
	v_lshlrev_b32_e32 v116, 16, v27
	v_and_b32_e32 v113, 0xffff0000, v26
	v_lshlrev_b32_e32 v124, 16, v30
	v_and_b32_e32 v125, 0xffff0000, v30
	s_waitcnt lgkmcnt(0)
	v_lshlrev_b32_e32 v122, 16, v29
	v_and_b32_e32 v123, 0xffff0000, v29
	s_ashr_i32 s13, s12, 31
	s_lshl_b64 s[20:21], s[12:13], 11
	s_waitcnt lgkmcnt(0)
	v_lshlrev_b32_e32 v126, 16, v31
	s_waitcnt lgkmcnt(0)
	v_mov_b32_e32 v96, s98
	v_fmamk_f32 v96, v96, 0x3a800000, v79
	v_rsq_f32_e32 v96, v96
	v_mov_b32_e32 v130, v102
	v_mov_b32_e32 v111, v132
	v_pk_mul_f32 v[98:99], v[96:97], v[98:99] op_sel_hi:[0,1]
	v_pk_fma_f32 v[82:83], v[202:203], v[98:99], v[106:107]
	v_pk_mul_f32 v[98:99], v[96:97], v[104:105] op_sel_hi:[0,1]
	v_pk_mul_f32 v[128:129], v[96:97], v[128:129] op_sel_hi:[0,1]
	v_pk_mul_f32 v[130:131], v[96:97], v[130:131] op_sel_hi:[0,1]
	v_pk_fma_f32 v[80:81], v[200:201], v[128:129], v[100:101]
	v_pk_mul_f32 v[100:101], v[114:115], v[96:97] op_sel_hi:[1,0]
	v_pk_fma_f32 v[86:87], v[206:207], v[98:99], v[116:117]
	v_pk_mul_f32 v[98:99], v[108:109], v[96:97] op_sel_hi:[1,0]
	v_pk_fma_f32 v[84:85], v[204:205], v[130:131], v[112:113]
	v_pk_fma_f32 v[88:89], v[208:209], v[98:99], v[120:121]
	v_pk_mul_f32 v[98:99], v[110:111], v[96:97] op_sel_hi:[1,0]
	v_pk_mul_f32 v[96:97], v[118:119], v[96:97] op_sel_hi:[1,0]
	v_pk_fma_f32 v[90:91], v[210:211], v[100:101], v[122:123]
	v_pk_fma_f32 v[94:95], v[214:215], v[96:97], v[126:127]
	v_mul_f32_e32 v96, v81, v81
	v_mul_f32_e32 v97, v83, v83
	v_fmac_f32_e32 v96, v80, v80
	v_fmac_f32_e32 v97, v82, v82
	v_pk_fma_f32 v[92:93], v[212:213], v[98:99], v[124:125]
	v_add_f32_e32 v96, v96, v97
	v_mul_f32_e32 v97, v85, v85
	v_mul_f32_e32 v98, v87, v87
	v_fmac_f32_e32 v97, v84, v84
	v_fmac_f32_e32 v98, v86, v86
	v_add_f32_e32 v97, v97, v98
	v_add_f32_e32 v96, v96, v97
	v_mul_f32_e32 v97, v89, v89
	v_mul_f32_e32 v98, v91, v91
	v_fmac_f32_e32 v97, v88, v88
	v_fmac_f32_e32 v98, v90, v90
	v_add_f32_e32 v97, v97, v98
	v_add_f32_e32 v96, v97, v96
	v_mul_f32_e32 v97, v93, v93
	v_mul_f32_e32 v98, v95, v95
	v_fmac_f32_e32 v97, v92, v92
	v_fmac_f32_e32 v98, v94, v94
	v_add_f32_e32 v97, v97, v98
	v_add_f32_e32 v96, v97, v96
	s_nop 1
	v_add_f32_dpp v240, v96, v96 quad_perm:[1,0,3,2] row_mask:0xf bank_mask:0xf
	s_nop 1
	v_add_f32_dpp v240, v240, v240 quad_perm:[2,3,0,1] row_mask:0xf bank_mask:0xf
	s_nop 1
	v_add_f32_dpp v240, v240, v240 row_half_mirror row_mask:0xf bank_mask:0xf
	s_nop 1
	v_add_f32_dpp v240, v240, v240 row_mirror row_mask:0xf bank_mask:0xf
	s_nop 1
	v_add_f32_dpp v240, v240, v240 row_bcast:15 row_mask:0xa bank_mask:0xf
	s_nop 1
	v_add_f32_dpp v240, v240, v240 row_bcast:31 row_mask:0xc bank_mask:0xf
	s_nop 0
	v_readlane_b32 s98, v240, 63
	s_nop 1
	v_cvt_pk_bf16_f32 v80, v80, v81
	v_cvt_pk_bf16_f32 v81, v82, v83
	s_waitcnt lgkmcnt(0)
	s_waitcnt lgkmcnt(0)
	v_lshl_add_u64 v[96:97], v[42:43], 0, s[20:21]
	global_store_dwordx2 v[96:97], v[80:81], off sc1
	v_cvt_pk_bf16_f32 v80, v84, v85
	v_cvt_pk_bf16_f32 v81, v86, v87
	s_waitcnt lgkmcnt(0)
	global_store_dwordx2 v[96:97], v[80:81], off offset:512 sc1
	v_cvt_pk_bf16_f32 v82, v88, v89
	v_cvt_pk_bf16_f32 v83, v90, v91
	global_store_dwordx2 v[96:97], v[82:83], off offset:1024 sc1
	s_waitcnt lgkmcnt(0)
	v_cvt_pk_bf16_f32 v82, v92, v93
	v_cvt_pk_bf16_f32 v83, v94, v95
	global_store_dwordx2 v[96:97], v[82:83], off offset:1536 sc1
	s_waitcnt lgkmcnt(0)
	s_and_saveexec_b64 s[20:21], s[4:5]
	s_cbranch_execz .LBB0_707
	s_waitcnt lgkmcnt(0)
	v_mov_b32_e32 v80, s98
	v_fmamk_f32 v80, v80, 0x3a800000, v79
	v_rsq_f32_e32 v80, v80
	s_lshl_b64 s[28:29], s[12:13], 2
	s_add_u32 s28, s22, s28
	s_addc_u32 s29, s23, s29
	global_store_dword v19, v80, s[28:29] sc1
.LBB0_707:
	s_or_b64 exec, exec, s[20:21]
	v_and_b32_e32 v99, 0xffff0000, v53
	v_and_b32_e32 v98, 0xffff0000, v52
	v_lshlrev_b32_e32 v97, 16, v53
	v_lshlrev_b32_e32 v96, 16, v52
	v_pk_mul_f32 v[84:85], v[98:99], v[98:99]
	s_waitcnt lgkmcnt(0)
	v_pk_fma_f32 v[84:85], v[96:97], v[96:97], v[84:85]
	v_and_b32_e32 v105, 0xffff0000, v55
	v_and_b32_e32 v104, 0xffff0000, v54
	v_pk_add_f32 v[100:101], v[84:85], v[84:85] op_sel_hi:[0,1]
	v_lshlrev_b32_e32 v103, 16, v55
	v_lshlrev_b32_e32 v102, 16, v54
	v_pk_mul_f32 v[92:93], v[104:105], v[104:105]
	v_pk_fma_f32 v[92:93], v[102:103], v[102:103], v[92:93]
	v_lshlrev_b32_e32 v108, 16, v56
	v_pk_add_f32 v[106:107], v[92:93], v[92:93] op_sel_hi:[0,1]
	v_and_b32_e32 v109, 0xffff0000, v56
	v_lshlrev_b32_e32 v114, 16, v57
	v_lshlrev_b32_e32 v110, 16, v58
	v_mul_f32_e32 v111, v108, v108
	v_mul_f32_e32 v113, v109, v109
	v_and_b32_e32 v115, 0xffff0000, v57
	v_mul_f32_e32 v100, v114, v114
	v_mov_b32_e32 v112, v110
	v_pk_fma_f32 v[116:117], v[114:115], v[114:115], v[100:101] op_sel_hi:[1,1,0]
	v_and_b32_e32 v132, 0xffff0000, v58
	v_lshlrev_b32_e32 v118, 16, v59
	v_and_b32_e32 v119, 0xffff0000, v59
	v_pk_add_f32 v[112:113], v[110:111], v[112:113]
	v_mul_f32_e32 v116, v132, v132
	v_mul_f32_e32 v100, v118, v118
	v_mul_f32_e32 v106, v119, v119
	v_mul_f32_e32 v120, v110, v110
	v_mov_b32_e32 v121, v113
	v_pk_add_f32 v[112:113], v[120:121], v[116:117]
	v_pk_add_f32 v[100:101], v[100:101], v[106:107]
	v_mov_b32_e32 v128, v96
	v_pk_add_f32 v[100:101], v[112:113], v[100:101]
	v_mov_b32_e32 v129, v98
	v_add_f32_e32 v100, v100, v101
	s_nop 1
	v_add_f32_dpp v240, v100, v100 quad_perm:[1,0,3,2] row_mask:0xf bank_mask:0xf
	s_nop 1
	v_add_f32_dpp v240, v240, v240 quad_perm:[2,3,0,1] row_mask:0xf bank_mask:0xf
	s_nop 1
	v_add_f32_dpp v240, v240, v240 row_half_mirror row_mask:0xf bank_mask:0xf
	s_nop 1
	v_add_f32_dpp v240, v240, v240 row_mirror row_mask:0xf bank_mask:0xf
	s_nop 1
	v_add_f32_dpp v240, v240, v240 row_bcast:15 row_mask:0xa bank_mask:0xf
	s_nop 1
	v_add_f32_dpp v240, v240, v240 row_bcast:31 row_mask:0xc bank_mask:0xf
	s_nop 0
	v_readlane_b32 s98, v240, 63
	s_nop 1
	v_mov_b32_e32 v98, v97
	v_mov_b32_e32 v131, v104
	v_mov_b32_e32 v104, v103
	v_and_b32_e32 v117, 0xffff0000, v47
	s_waitcnt lgkmcnt(0)
	v_lshlrev_b32_e32 v100, 16, v44
	v_and_b32_e32 v101, 0xffff0000, v44
	v_lshlrev_b32_e32 v120, 16, v48
	v_and_b32_e32 v121, 0xffff0000, v48
	s_waitcnt lgkmcnt(0)
	v_lshlrev_b32_e32 v106, 16, v45
	v_and_b32_e32 v107, 0xffff0000, v45
	v_and_b32_e32 v127, 0xffff0000, v51
	v_lshlrev_b32_e32 v112, 16, v46
	s_waitcnt lgkmcnt(0)
	v_lshlrev_b32_e32 v116, 16, v47
	v_and_b32_e32 v113, 0xffff0000, v46
	v_lshlrev_b32_e32 v124, 16, v50
	v_and_b32_e32 v125, 0xffff0000, v50
	s_waitcnt lgkmcnt(0)
	v_lshlrev_b32_e32 v122, 16, v49
	v_and_b32_e32 v123, 0xffff0000, v49
	s_ashr_i32 s7, s6, 31
	s_lshl_b64 s[20:21], s[6:7], 11
	s_waitcnt lgkmcnt(0)
	v_lshlrev_b32_e32 v126, 16, v51
	s_waitcnt lgkmcnt(0)
	v_mov_b32_e32 v96, s98
	v_fmamk_f32 v96, v96, 0x3a800000, v79
	v_rsq_f32_e32 v96, v96
	v_mov_b32_e32 v130, v102
	v_mov_b32_e32 v111, v132
	v_pk_mul_f32 v[98:99], v[96:97], v[98:99] op_sel_hi:[0,1]
	v_pk_fma_f32 v[82:83], v[202:203], v[98:99], v[106:107]
	v_pk_mul_f32 v[98:99], v[96:97], v[104:105] op_sel_hi:[0,1]
	v_pk_mul_f32 v[128:129], v[96:97], v[128:129] op_sel_hi:[0,1]
	v_pk_mul_f32 v[130:131], v[96:97], v[130:131] op_sel_hi:[0,1]
	v_pk_fma_f32 v[80:81], v[200:201], v[128:129], v[100:101]
	v_pk_mul_f32 v[100:101], v[114:115], v[96:97] op_sel_hi:[1,0]
	v_pk_fma_f32 v[86:87], v[206:207], v[98:99], v[116:117]
	v_pk_mul_f32 v[98:99], v[108:109], v[96:97] op_sel_hi:[1,0]
	v_pk_fma_f32 v[84:85], v[204:205], v[130:131], v[112:113]
	v_pk_fma_f32 v[88:89], v[208:209], v[98:99], v[120:121]
	v_pk_mul_f32 v[98:99], v[110:111], v[96:97] op_sel_hi:[1,0]
	v_pk_mul_f32 v[96:97], v[118:119], v[96:97] op_sel_hi:[1,0]
	v_pk_fma_f32 v[90:91], v[210:211], v[100:101], v[122:123]
	v_pk_fma_f32 v[94:95], v[214:215], v[96:97], v[126:127]
	v_mul_f32_e32 v96, v81, v81
	v_mul_f32_e32 v97, v83, v83
	v_fmac_f32_e32 v96, v80, v80
	v_fmac_f32_e32 v97, v82, v82
	v_pk_fma_f32 v[92:93], v[212:213], v[98:99], v[124:125]
	v_add_f32_e32 v96, v96, v97
	v_mul_f32_e32 v97, v85, v85
	v_mul_f32_e32 v98, v87, v87
	v_fmac_f32_e32 v97, v84, v84
	v_fmac_f32_e32 v98, v86, v86
	v_add_f32_e32 v97, v97, v98
	v_add_f32_e32 v96, v96, v97
	v_mul_f32_e32 v97, v89, v89
	v_mul_f32_e32 v98, v91, v91
	v_fmac_f32_e32 v97, v88, v88
	v_fmac_f32_e32 v98, v90, v90
	v_add_f32_e32 v97, v97, v98
	v_add_f32_e32 v96, v97, v96
	v_mul_f32_e32 v97, v93, v93
	v_mul_f32_e32 v98, v95, v95
	v_fmac_f32_e32 v97, v92, v92
	v_fmac_f32_e32 v98, v94, v94
	v_add_f32_e32 v97, v97, v98
	v_add_f32_e32 v96, v97, v96
	s_nop 1
	v_add_f32_dpp v240, v96, v96 quad_perm:[1,0,3,2] row_mask:0xf bank_mask:0xf
	s_nop 1
	v_add_f32_dpp v240, v240, v240 quad_perm:[2,3,0,1] row_mask:0xf bank_mask:0xf
	s_nop 1
	v_add_f32_dpp v240, v240, v240 row_half_mirror row_mask:0xf bank_mask:0xf
	s_nop 1
	v_add_f32_dpp v240, v240, v240 row_mirror row_mask:0xf bank_mask:0xf
	s_nop 1
	v_add_f32_dpp v240, v240, v240 row_bcast:15 row_mask:0xa bank_mask:0xf
	s_nop 1
	v_add_f32_dpp v240, v240, v240 row_bcast:31 row_mask:0xc bank_mask:0xf
	s_nop 0
	v_readlane_b32 s98, v240, 63
	s_nop 1
	v_cvt_pk_bf16_f32 v80, v80, v81
	v_cvt_pk_bf16_f32 v81, v82, v83
	s_waitcnt lgkmcnt(0)
	s_waitcnt lgkmcnt(0)
	v_lshl_add_u64 v[96:97], v[42:43], 0, s[20:21]
	global_store_dwordx2 v[96:97], v[80:81], off sc1
	v_cvt_pk_bf16_f32 v80, v84, v85
	v_cvt_pk_bf16_f32 v81, v86, v87
	s_waitcnt lgkmcnt(0)
	global_store_dwordx2 v[96:97], v[80:81], off offset:512 sc1
	v_cvt_pk_bf16_f32 v82, v88, v89
	v_cvt_pk_bf16_f32 v83, v90, v91
	global_store_dwordx2 v[96:97], v[82:83], off offset:1024 sc1
	s_waitcnt lgkmcnt(0)
	v_cvt_pk_bf16_f32 v82, v92, v93
	v_cvt_pk_bf16_f32 v83, v94, v95
	global_store_dwordx2 v[96:97], v[82:83], off offset:1536 sc1
	s_waitcnt lgkmcnt(0)
	s_and_saveexec_b64 s[20:21], s[4:5]
	s_cbranch_execnz .LBB0_710
	s_or_b64 exec, exec, s[20:21]
	s_waitcnt vmcnt(9)
	s_add_i32 s20, s24, s16
	s_cmpk_gt_i32 s20, 0x7fff
	s_cbranch_scc0 .LBB0_711

.LBB0_710:
	s_waitcnt lgkmcnt(0)
	v_mov_b32_e32 v80, s98
	v_fmamk_f32 v80, v80, 0x3a800000, v79
	v_rsq_f32_e32 v80, v80
	s_lshl_b64 s[28:29], s[6:7], 2
	s_add_u32 s28, s22, s28
	s_addc_u32 s29, s23, s29
	global_store_dword v19, v80, s[28:29] sc1
	s_waitcnt vmcnt(10)
	s_or_b64 exec, exec, s[20:21]
	s_add_i32 s20, s24, s16
	s_cmpk_gt_i32 s20, 0x7fff
	s_cbranch_scc1 .LBB0_709

.LBB0_712:
	v_and_b32_e32 v99, 0xffff0000, v17
	v_and_b32_e32 v98, 0xffff0000, v16
	v_lshlrev_b32_e32 v97, 16, v17
	v_lshlrev_b32_e32 v96, 16, v16
	v_pk_mul_f32 v[84:85], v[98:99], v[98:99]
	s_waitcnt lgkmcnt(0)
	v_pk_fma_f32 v[84:85], v[96:97], v[96:97], v[84:85]
	v_and_b32_e32 v105, 0xffff0000, v61
	v_and_b32_e32 v104, 0xffff0000, v60
	v_pk_add_f32 v[100:101], v[84:85], v[84:85] op_sel_hi:[0,1]
	v_lshlrev_b32_e32 v103, 16, v61
	v_lshlrev_b32_e32 v102, 16, v60
	v_pk_mul_f32 v[92:93], v[104:105], v[104:105]
	v_pk_fma_f32 v[92:93], v[102:103], v[102:103], v[92:93]
	v_lshlrev_b32_e32 v108, 16, v62
	v_pk_add_f32 v[106:107], v[92:93], v[92:93] op_sel_hi:[0,1]
	v_and_b32_e32 v109, 0xffff0000, v62
	v_lshlrev_b32_e32 v114, 16, v63
	v_lshlrev_b32_e32 v110, 16, v64
	v_mul_f32_e32 v111, v108, v108
	v_mul_f32_e32 v113, v109, v109
	v_and_b32_e32 v115, 0xffff0000, v63
	v_mul_f32_e32 v100, v114, v114
	v_mov_b32_e32 v112, v110
	v_pk_fma_f32 v[116:117], v[114:115], v[114:115], v[100:101] op_sel_hi:[1,1,0]
	v_and_b32_e32 v132, 0xffff0000, v64
	v_lshlrev_b32_e32 v118, 16, v65
	v_and_b32_e32 v119, 0xffff0000, v65
	v_pk_add_f32 v[112:113], v[110:111], v[112:113]
	v_mul_f32_e32 v116, v132, v132
	v_mul_f32_e32 v106, v118, v118
	v_mul_f32_e32 v100, v119, v119
	v_mul_f32_e32 v120, v110, v110
	v_mov_b32_e32 v121, v113
	v_pk_add_f32 v[112:113], v[120:121], v[116:117]
	v_pk_add_f32 v[100:101], v[106:107], v[100:101]
	v_mov_b32_e32 v128, v96
	v_pk_add_f32 v[100:101], v[112:113], v[100:101]
	v_mov_b32_e32 v129, v98
	v_add_f32_e32 v100, v100, v101
	s_nop 1
	v_add_f32_dpp v240, v100, v100 quad_perm:[1,0,3,2] row_mask:0xf bank_mask:0xf
	s_nop 1
	v_add_f32_dpp v240, v240, v240 quad_perm:[2,3,0,1] row_mask:0xf bank_mask:0xf
	s_nop 1
	v_add_f32_dpp v240, v240, v240 row_half_mirror row_mask:0xf bank_mask:0xf
	s_nop 1
	v_add_f32_dpp v240, v240, v240 row_mirror row_mask:0xf bank_mask:0xf
	s_nop 1
	v_add_f32_dpp v240, v240, v240 row_bcast:15 row_mask:0xa bank_mask:0xf
	s_nop 1
	v_add_f32_dpp v240, v240, v240 row_bcast:31 row_mask:0xc bank_mask:0xf
	s_nop 0
	v_readlane_b32 s98, v240, 63
	s_nop 1
	v_mov_b32_e32 v98, v97
	v_mov_b32_e32 v131, v104
	v_mov_b32_e32 v104, v103
	v_and_b32_e32 v117, 0xffff0000, v3
	s_waitcnt lgkmcnt(0)
	v_lshlrev_b32_e32 v100, 16, v0
	v_and_b32_e32 v101, 0xffff0000, v0
	v_lshlrev_b32_e32 v120, 16, v4
	v_and_b32_e32 v121, 0xffff0000, v4
	s_waitcnt lgkmcnt(0)
	v_lshlrev_b32_e32 v106, 16, v1
	v_and_b32_e32 v107, 0xffff0000, v1
	v_and_b32_e32 v127, 0xffff0000, v7
	v_lshlrev_b32_e32 v112, 16, v2
	s_waitcnt lgkmcnt(0)
	v_lshlrev_b32_e32 v116, 16, v3
	v_and_b32_e32 v113, 0xffff0000, v2
	v_lshlrev_b32_e32 v124, 16, v6
	v_and_b32_e32 v125, 0xffff0000, v6
	s_waitcnt lgkmcnt(0)
	v_lshlrev_b32_e32 v122, 16, v5
	v_and_b32_e32 v123, 0xffff0000, v5
	s_ashr_i32 s11, s10, 31
	s_lshl_b64 s[16:17], s[10:11], 11
	s_waitcnt lgkmcnt(0)
	v_lshlrev_b32_e32 v126, 16, v7
	s_waitcnt lgkmcnt(0)
	v_mov_b32_e32 v96, s98
	v_fmamk_f32 v96, v96, 0x3a800000, v79
	v_rsq_f32_e32 v96, v96
	v_mov_b32_e32 v130, v102
	v_mov_b32_e32 v111, v132
	v_pk_mul_f32 v[98:99], v[96:97], v[98:99] op_sel_hi:[0,1]
	v_pk_fma_f32 v[82:83], v[202:203], v[98:99], v[106:107]
	v_pk_mul_f32 v[98:99], v[96:97], v[104:105] op_sel_hi:[0,1]
	v_pk_mul_f32 v[128:129], v[96:97], v[128:129] op_sel_hi:[0,1]
	v_pk_mul_f32 v[130:131], v[96:97], v[130:131] op_sel_hi:[0,1]
	v_pk_fma_f32 v[80:81], v[200:201], v[128:129], v[100:101]
	v_pk_mul_f32 v[100:101], v[114:115], v[96:97] op_sel_hi:[1,0]
	v_pk_fma_f32 v[86:87], v[206:207], v[98:99], v[116:117]
	v_pk_mul_f32 v[98:99], v[108:109], v[96:97] op_sel_hi:[1,0]
	v_pk_fma_f32 v[84:85], v[204:205], v[130:131], v[112:113]
	v_pk_fma_f32 v[88:89], v[208:209], v[98:99], v[120:121]
	v_pk_mul_f32 v[98:99], v[110:111], v[96:97] op_sel_hi:[1,0]
	v_pk_mul_f32 v[96:97], v[118:119], v[96:97] op_sel_hi:[1,0]
	v_pk_fma_f32 v[90:91], v[210:211], v[100:101], v[122:123]
	v_pk_fma_f32 v[94:95], v[214:215], v[96:97], v[126:127]
	v_mul_f32_e32 v96, v81, v81
	v_mul_f32_e32 v97, v83, v83
	v_fmac_f32_e32 v96, v80, v80
	v_fmac_f32_e32 v97, v82, v82
	v_pk_fma_f32 v[92:93], v[212:213], v[98:99], v[124:125]
	v_add_f32_e32 v96, v96, v97
	v_mul_f32_e32 v97, v85, v85
	v_mul_f32_e32 v98, v87, v87
	v_fmac_f32_e32 v97, v84, v84
	v_fmac_f32_e32 v98, v86, v86
	v_add_f32_e32 v97, v97, v98
	v_add_f32_e32 v96, v96, v97
	v_mul_f32_e32 v97, v89, v89
	v_mul_f32_e32 v98, v91, v91
	v_fmac_f32_e32 v97, v88, v88
	v_fmac_f32_e32 v98, v90, v90
	v_add_f32_e32 v97, v97, v98
	v_add_f32_e32 v96, v97, v96
	v_mul_f32_e32 v97, v93, v93
	v_mul_f32_e32 v98, v95, v95
	v_fmac_f32_e32 v97, v92, v92
	v_fmac_f32_e32 v98, v94, v94
	v_add_f32_e32 v97, v97, v98
	v_add_f32_e32 v96, v97, v96
	s_nop 1
	v_add_f32_dpp v240, v96, v96 quad_perm:[1,0,3,2] row_mask:0xf bank_mask:0xf
	s_nop 1
	v_add_f32_dpp v240, v240, v240 quad_perm:[2,3,0,1] row_mask:0xf bank_mask:0xf
	s_nop 1
	v_add_f32_dpp v240, v240, v240 row_half_mirror row_mask:0xf bank_mask:0xf
	s_nop 1
	v_add_f32_dpp v240, v240, v240 row_mirror row_mask:0xf bank_mask:0xf
	s_nop 1
	v_add_f32_dpp v240, v240, v240 row_bcast:15 row_mask:0xa bank_mask:0xf
	s_nop 1
	v_add_f32_dpp v240, v240, v240 row_bcast:31 row_mask:0xc bank_mask:0xf
	s_nop 0
	v_readlane_b32 s98, v240, 63
	s_nop 1
	v_cvt_pk_bf16_f32 v80, v80, v81
	v_cvt_pk_bf16_f32 v81, v82, v83
	s_waitcnt lgkmcnt(0)
	s_waitcnt lgkmcnt(0)
	v_lshl_add_u64 v[96:97], v[42:43], 0, s[16:17]
	global_store_dwordx2 v[96:97], v[80:81], off sc1
	v_cvt_pk_bf16_f32 v80, v84, v85
	v_cvt_pk_bf16_f32 v81, v86, v87
	s_waitcnt lgkmcnt(0)
	global_store_dwordx2 v[96:97], v[80:81], off offset:512 sc1
	v_cvt_pk_bf16_f32 v82, v88, v89
	v_cvt_pk_bf16_f32 v83, v90, v91
	global_store_dwordx2 v[96:97], v[82:83], off offset:1024 sc1
	s_waitcnt lgkmcnt(0)
	v_cvt_pk_bf16_f32 v82, v92, v93
	v_cvt_pk_bf16_f32 v83, v94, v95
	global_store_dwordx2 v[96:97], v[82:83], off offset:1536 sc1
	s_waitcnt lgkmcnt(0)
	s_and_saveexec_b64 s[16:17], s[4:5]
	s_cbranch_execz .LBB0_714
	s_waitcnt lgkmcnt(0)
	v_mov_b32_e32 v80, s98
	v_fmamk_f32 v80, v80, 0x3a800000, v79
	v_rsq_f32_e32 v80, v80
	s_lshl_b64 s[18:19], s[10:11], 2
	s_add_u32 s18, s22, s18
	s_addc_u32 s19, s23, s19
	global_store_dword v19, v80, s[18:19] sc1
.LBB0_714:
	s_or_b64 exec, exec, s[16:17]
	v_and_b32_e32 v99, 0xffff0000, v67
	v_and_b32_e32 v98, 0xffff0000, v66
	v_lshlrev_b32_e32 v97, 16, v67
	v_lshlrev_b32_e32 v96, 16, v66
	v_pk_mul_f32 v[84:85], v[98:99], v[98:99]
	s_waitcnt lgkmcnt(0)
	v_pk_fma_f32 v[84:85], v[96:97], v[96:97], v[84:85]
	v_and_b32_e32 v105, 0xffff0000, v69
	v_and_b32_e32 v104, 0xffff0000, v68
	v_pk_add_f32 v[100:101], v[84:85], v[84:85] op_sel_hi:[0,1]
	v_lshlrev_b32_e32 v103, 16, v69
	v_lshlrev_b32_e32 v102, 16, v68
	v_pk_mul_f32 v[92:93], v[104:105], v[104:105]
	v_pk_fma_f32 v[92:93], v[102:103], v[102:103], v[92:93]
	v_lshlrev_b32_e32 v108, 16, v70
	v_pk_add_f32 v[106:107], v[92:93], v[92:93] op_sel_hi:[0,1]
	v_and_b32_e32 v109, 0xffff0000, v70
	v_lshlrev_b32_e32 v114, 16, v71
	v_lshlrev_b32_e32 v110, 16, v72
	v_mul_f32_e32 v111, v108, v108
	v_mul_f32_e32 v113, v109, v109
	v_and_b32_e32 v115, 0xffff0000, v71
	v_mul_f32_e32 v100, v114, v114
	v_mov_b32_e32 v112, v110
	v_pk_fma_f32 v[116:117], v[114:115], v[114:115], v[100:101] op_sel_hi:[1,1,0]
	v_and_b32_e32 v132, 0xffff0000, v72
	v_lshlrev_b32_e32 v118, 16, v73
	v_and_b32_e32 v119, 0xffff0000, v73
	v_pk_add_f32 v[112:113], v[110:111], v[112:113]
	v_mul_f32_e32 v116, v132, v132
	v_mul_f32_e32 v106, v118, v118
	v_mul_f32_e32 v100, v119, v119
	v_mul_f32_e32 v120, v110, v110
	v_mov_b32_e32 v121, v113
	v_pk_add_f32 v[112:113], v[120:121], v[116:117]
	v_pk_add_f32 v[100:101], v[106:107], v[100:101]
	v_mov_b32_e32 v128, v96
	v_pk_add_f32 v[100:101], v[112:113], v[100:101]
	v_mov_b32_e32 v129, v98
	v_add_f32_e32 v100, v100, v101
	s_nop 1
	v_add_f32_dpp v240, v100, v100 quad_perm:[1,0,3,2] row_mask:0xf bank_mask:0xf
	s_nop 1
	v_add_f32_dpp v240, v240, v240 quad_perm:[2,3,0,1] row_mask:0xf bank_mask:0xf
	s_nop 1
	v_add_f32_dpp v240, v240, v240 row_half_mirror row_mask:0xf bank_mask:0xf
	s_nop 1
	v_add_f32_dpp v240, v240, v240 row_mirror row_mask:0xf bank_mask:0xf
	s_nop 1
	v_add_f32_dpp v240, v240, v240 row_bcast:15 row_mask:0xa bank_mask:0xf
	s_nop 1
	v_add_f32_dpp v240, v240, v240 row_bcast:31 row_mask:0xc bank_mask:0xf
	s_nop 0
	v_readlane_b32 s98, v240, 63
	s_nop 1
	v_mov_b32_e32 v98, v97
	v_mov_b32_e32 v131, v104
	v_mov_b32_e32 v104, v103
	v_and_b32_e32 v117, 0xffff0000, v11
	s_waitcnt lgkmcnt(0)
	v_lshlrev_b32_e32 v100, 16, v8
	v_and_b32_e32 v101, 0xffff0000, v8
	v_lshlrev_b32_e32 v120, 16, v12
	v_and_b32_e32 v121, 0xffff0000, v12
	s_waitcnt lgkmcnt(0)
	v_lshlrev_b32_e32 v106, 16, v9
	v_and_b32_e32 v107, 0xffff0000, v9
	v_and_b32_e32 v127, 0xffff0000, v15
	v_lshlrev_b32_e32 v112, 16, v10
	s_waitcnt lgkmcnt(0)
	v_lshlrev_b32_e32 v116, 16, v11
	v_and_b32_e32 v113, 0xffff0000, v10
	v_lshlrev_b32_e32 v124, 16, v14
	v_and_b32_e32 v125, 0xffff0000, v14
	s_waitcnt lgkmcnt(0)
	v_lshlrev_b32_e32 v122, 16, v13
	v_and_b32_e32 v123, 0xffff0000, v13
	s_ashr_i32 s9, s8, 31
	s_lshl_b64 s[16:17], s[8:9], 11
	s_waitcnt lgkmcnt(0)
	v_lshlrev_b32_e32 v126, 16, v15
	s_waitcnt lgkmcnt(0)
	v_mov_b32_e32 v96, s98
	v_fmamk_f32 v96, v96, 0x3a800000, v79
	v_rsq_f32_e32 v96, v96
	v_mov_b32_e32 v130, v102
	v_mov_b32_e32 v111, v132
	v_pk_mul_f32 v[98:99], v[96:97], v[98:99] op_sel_hi:[0,1]
	v_pk_fma_f32 v[82:83], v[202:203], v[98:99], v[106:107]
	v_pk_mul_f32 v[98:99], v[96:97], v[104:105] op_sel_hi:[0,1]
	v_pk_mul_f32 v[128:129], v[96:97], v[128:129] op_sel_hi:[0,1]
	v_pk_mul_f32 v[130:131], v[96:97], v[130:131] op_sel_hi:[0,1]
	v_pk_fma_f32 v[80:81], v[200:201], v[128:129], v[100:101]
	v_pk_mul_f32 v[100:101], v[114:115], v[96:97] op_sel_hi:[1,0]
	v_pk_fma_f32 v[86:87], v[206:207], v[98:99], v[116:117]
	v_pk_mul_f32 v[98:99], v[108:109], v[96:97] op_sel_hi:[1,0]
	v_pk_fma_f32 v[84:85], v[204:205], v[130:131], v[112:113]
	v_pk_fma_f32 v[88:89], v[208:209], v[98:99], v[120:121]
	v_pk_mul_f32 v[98:99], v[110:111], v[96:97] op_sel_hi:[1,0]
	v_pk_mul_f32 v[96:97], v[118:119], v[96:97] op_sel_hi:[1,0]
	v_pk_fma_f32 v[90:91], v[210:211], v[100:101], v[122:123]
	v_pk_fma_f32 v[94:95], v[214:215], v[96:97], v[126:127]
	v_mul_f32_e32 v96, v81, v81
	v_mul_f32_e32 v97, v83, v83
	v_fmac_f32_e32 v96, v80, v80
	v_fmac_f32_e32 v97, v82, v82
	v_pk_fma_f32 v[92:93], v[212:213], v[98:99], v[124:125]
	v_add_f32_e32 v96, v96, v97
	v_mul_f32_e32 v97, v85, v85
	v_mul_f32_e32 v98, v87, v87
	v_fmac_f32_e32 v97, v84, v84
	v_fmac_f32_e32 v98, v86, v86
	v_add_f32_e32 v97, v97, v98
	v_add_f32_e32 v96, v96, v97
	v_mul_f32_e32 v97, v89, v89
	v_mul_f32_e32 v98, v91, v91
	v_fmac_f32_e32 v97, v88, v88
	v_fmac_f32_e32 v98, v90, v90
	v_add_f32_e32 v97, v97, v98
	v_add_f32_e32 v96, v97, v96
	v_mul_f32_e32 v97, v93, v93
	v_mul_f32_e32 v98, v95, v95
	v_fmac_f32_e32 v97, v92, v92
	v_fmac_f32_e32 v98, v94, v94
	v_add_f32_e32 v97, v97, v98
	v_add_f32_e32 v96, v97, v96
	s_nop 1
	v_add_f32_dpp v240, v96, v96 quad_perm:[1,0,3,2] row_mask:0xf bank_mask:0xf
	s_nop 1
	v_add_f32_dpp v240, v240, v240 quad_perm:[2,3,0,1] row_mask:0xf bank_mask:0xf
	s_nop 1
	v_add_f32_dpp v240, v240, v240 row_half_mirror row_mask:0xf bank_mask:0xf
	s_nop 1
	v_add_f32_dpp v240, v240, v240 row_mirror row_mask:0xf bank_mask:0xf
	s_nop 1
	v_add_f32_dpp v240, v240, v240 row_bcast:15 row_mask:0xa bank_mask:0xf
	s_nop 1
	v_add_f32_dpp v240, v240, v240 row_bcast:31 row_mask:0xc bank_mask:0xf
	s_nop 0
	v_readlane_b32 s98, v240, 63
	s_nop 1
	v_cvt_pk_bf16_f32 v80, v80, v81
	v_cvt_pk_bf16_f32 v81, v82, v83
	s_waitcnt lgkmcnt(0)
	s_waitcnt lgkmcnt(0)
	v_lshl_add_u64 v[96:97], v[42:43], 0, s[16:17]
	global_store_dwordx2 v[96:97], v[80:81], off sc1
	v_cvt_pk_bf16_f32 v80, v84, v85
	v_cvt_pk_bf16_f32 v81, v86, v87
	s_waitcnt lgkmcnt(0)
	global_store_dwordx2 v[96:97], v[80:81], off offset:512 sc1
	v_cvt_pk_bf16_f32 v82, v88, v89
	v_cvt_pk_bf16_f32 v83, v90, v91
	global_store_dwordx2 v[96:97], v[82:83], off offset:1024 sc1
	s_waitcnt lgkmcnt(0)
	v_cvt_pk_bf16_f32 v82, v92, v93
	v_cvt_pk_bf16_f32 v83, v94, v95
	global_store_dwordx2 v[96:97], v[82:83], off offset:1536 sc1
	s_waitcnt lgkmcnt(0)
	s_and_saveexec_b64 s[16:17], s[4:5]
	s_cbranch_execz .LBB0_701
	s_waitcnt lgkmcnt(0)
	v_mov_b32_e32 v80, s98
	v_fmamk_f32 v80, v80, 0x3a800000, v79
	v_rsq_f32_e32 v80, v80
	s_lshl_b64 s[18:19], s[8:9], 2
	s_add_u32 s18, s22, s18
	s_addc_u32 s19, s23, s19
	global_store_dword v19, v80, s[18:19] sc1
	s_branch .LBB0_701

.LBB0_1455:
	s_nop 0
	v_and_b32_e32 v73, 0xffff0000, v30
	v_and_b32_e32 v75, 0xffff0000, v31
	v_lshlrev_b32_e32 v72, 16, v30
	v_lshlrev_b32_e32 v74, 16, v31
	v_mul_f32_e32 v76, v73, v73
	v_mul_f32_e32 v77, v75, v75
	v_fmac_f32_e32 v76, v72, v72
	v_fmac_f32_e32 v77, v74, v74
	v_add_f32_e32 v80, v76, v77
	s_nop 0
	v_and_b32_e32 v77, 0xffff0000, v32
	v_and_b32_e32 v79, 0xffff0000, v33
	v_lshlrev_b32_e32 v76, 16, v32
	v_lshlrev_b32_e32 v78, 16, v33
	v_mul_f32_e32 v81, v77, v77
	v_mul_f32_e32 v82, v79, v79
	v_fmac_f32_e32 v81, v76, v76
	v_fmac_f32_e32 v82, v78, v78
	v_add_f32_e32 v81, v81, v82
	v_add_f32_e32 v84, v80, v81
	s_nop 0
	v_and_b32_e32 v81, 0xffff0000, v34
	v_and_b32_e32 v83, 0xffff0000, v35
	v_lshlrev_b32_e32 v80, 16, v34
	v_lshlrev_b32_e32 v82, 16, v35
	v_mul_f32_e32 v85, v81, v81
	v_mul_f32_e32 v86, v83, v83
	v_fmac_f32_e32 v85, v80, v80
	v_fmac_f32_e32 v86, v82, v82
	v_add_f32_e32 v85, v85, v86
	v_add_f32_e32 v95, v85, v84
	s_nop 0
	v_and_b32_e32 v85, 0xffff0000, v36
	v_and_b32_e32 v87, 0xffff0000, v37
	v_lshlrev_b32_e32 v84, 16, v36
	v_lshlrev_b32_e32 v86, 16, v37
	s_waitcnt lgkmcnt(0)
	v_mul_f32_e32 v96, v85, v85
	v_mul_f32_e32 v97, v87, v87
	v_fmac_f32_e32 v96, v84, v84
	v_fmac_f32_e32 v97, v86, v86
	v_add_f32_e32 v96, v96, v97
	v_add_f32_e32 v95, v96, v95
	s_nop 1
	v_add_f32_dpp v240, v95, v95 quad_perm:[1,0,3,2] row_mask:0xf bank_mask:0xf
	s_nop 1
	v_add_f32_dpp v240, v240, v240 quad_perm:[2,3,0,1] row_mask:0xf bank_mask:0xf
	s_nop 1
	v_add_f32_dpp v240, v240, v240 row_half_mirror row_mask:0xf bank_mask:0xf
	s_nop 1
	v_add_f32_dpp v240, v240, v240 row_mirror row_mask:0xf bank_mask:0xf
	s_nop 1
	v_add_f32_dpp v240, v240, v240 row_bcast:15 row_mask:0xa bank_mask:0xf
	s_nop 1
	v_add_f32_dpp v240, v240, v240 row_bcast:31 row_mask:0xc bank_mask:0xf
	s_nop 0
	v_readlane_b32 s98, v240, 63
	s_nop 1
	v_cndmask_b32_e64 v97, 0, 1, s[4:5]
	v_cmp_ne_u32_e64 s[0:1], 1, v97
	s_andn2_b64 vcc, exec, s[4:5]
	s_waitcnt lgkmcnt(0)
	s_waitcnt lgkmcnt(0)
	s_waitcnt lgkmcnt(0)
	s_waitcnt lgkmcnt(0)
	s_waitcnt lgkmcnt(0)
	s_cbranch_vccnz .LBB0_1457
	s_waitcnt lgkmcnt(0)
	v_mov_b32_e32 v95, s98
	v_fmamk_f32 v95, v95, 0x3a800000, v94
	v_rsq_f32_e32 v128, v95
	s_ashr_i32 s11, s10, 31
	v_lshlrev_b32_e32 v116, 16, v26
	v_and_b32_e32 v117, 0xffff0000, v26
	v_lshlrev_b32_e32 v118, 16, v27
	v_and_b32_e32 v119, 0xffff0000, v27
	v_lshlrev_b32_e32 v120, 16, v22
	v_and_b32_e32 v121, 0xffff0000, v22
	v_lshlrev_b32_e32 v122, 16, v23
	v_and_b32_e32 v123, 0xffff0000, v23
	s_lshl_b64 s[18:19], s[10:11], 12
	v_pk_mul_f32 v[80:81], v[80:81], v[128:129] op_sel_hi:[1,0]
	v_pk_mul_f32 v[82:83], v[82:83], v[128:129] op_sel_hi:[1,0]
	v_pk_mul_f32 v[132:133], v[72:73], v[128:129] op_sel_hi:[1,0]
	v_pk_mul_f32 v[134:135], v[74:75], v[128:129] op_sel_hi:[1,0]
	v_lshlrev_b32_e32 v96, 16, v28
	v_and_b32_e32 v97, 0xffff0000, v28
	v_lshlrev_b32_e32 v114, 16, v29
	v_and_b32_e32 v115, 0xffff0000, v29
	v_lshlrev_b32_e32 v124, 16, v24
	v_and_b32_e32 v125, 0xffff0000, v24
	v_lshlrev_b32_e32 v126, 16, v25
	v_and_b32_e32 v127, 0xffff0000, v25
	v_lshl_add_u64 v[130:131], v[40:41], 0, s[18:19]
	v_pk_mul_f32 v[84:85], v[84:85], v[128:129] op_sel_hi:[1,0]
	v_pk_mul_f32 v[86:87], v[86:87], v[128:129] op_sel_hi:[1,0]
	v_pk_mul_f32 v[136:137], v[76:77], v[128:129] op_sel_hi:[1,0]
	v_pk_mul_f32 v[128:129], v[78:79], v[128:129] op_sel_hi:[1,0]
	s_nop 0
	v_pk_fma_f32 v[74:75], v[86:87], v[100:101], v[114:115]
	s_nop 0
	v_pk_fma_f32 v[78:79], v[82:83], v[104:105], v[118:119]
	v_pk_fma_f32 v[76:77], v[80:81], v[102:103], v[116:117]
	s_nop 0
	v_pk_fma_f32 v[82:83], v[134:135], v[108:109], v[122:123]
	v_pk_fma_f32 v[80:81], v[132:133], v[106:107], v[120:121]
	v_pk_fma_f32 v[72:73], v[84:85], v[98:99], v[96:97]
	s_nop 0
	v_pk_fma_f32 v[86:87], v[128:129], v[112:113], v[126:127]
	v_pk_fma_f32 v[84:85], v[136:137], v[110:111], v[124:125]
	global_store_dwordx4 v[130:131], v[80:83], off
	global_store_dwordx4 v[130:131], v[84:87], off offset:1024
	global_store_dwordx4 v[130:131], v[76:79], off offset:2048
	global_store_dwordx4 v[130:131], v[72:75], off offset:3072
.LBB0_1457:
	s_nop 0
	s_nop 0
	v_and_b32_e32 v73, 0xffff0000, v50
	v_and_b32_e32 v75, 0xffff0000, v51
	v_lshlrev_b32_e32 v72, 16, v50
	v_lshlrev_b32_e32 v74, 16, v51
	v_mul_f32_e32 v76, v73, v73
	v_mul_f32_e32 v77, v75, v75
	v_fmac_f32_e32 v76, v72, v72
	v_fmac_f32_e32 v77, v74, v74
	v_add_f32_e32 v80, v76, v77
	s_nop 0
	v_and_b32_e32 v77, 0xffff0000, v52
	v_and_b32_e32 v79, 0xffff0000, v53
	v_lshlrev_b32_e32 v76, 16, v52
	v_lshlrev_b32_e32 v78, 16, v53
	v_mul_f32_e32 v81, v77, v77
	v_mul_f32_e32 v82, v79, v79
	v_fmac_f32_e32 v81, v76, v76
	v_fmac_f32_e32 v82, v78, v78
	v_add_f32_e32 v81, v81, v82
	v_add_f32_e32 v84, v80, v81
	s_nop 0
	v_and_b32_e32 v81, 0xffff0000, v54
	v_and_b32_e32 v83, 0xffff0000, v55
	v_lshlrev_b32_e32 v80, 16, v54
	v_lshlrev_b32_e32 v82, 16, v55
	v_mul_f32_e32 v85, v81, v81
	v_mul_f32_e32 v86, v83, v83
	v_fmac_f32_e32 v85, v80, v80
	v_fmac_f32_e32 v86, v82, v82
	v_add_f32_e32 v85, v85, v86
	v_add_f32_e32 v95, v85, v84
	s_nop 0
	v_and_b32_e32 v85, 0xffff0000, v56
	v_and_b32_e32 v87, 0xffff0000, v57
	v_lshlrev_b32_e32 v84, 16, v56
	v_lshlrev_b32_e32 v86, 16, v57
	s_waitcnt lgkmcnt(0)
	v_mul_f32_e32 v96, v85, v85
	v_mul_f32_e32 v97, v87, v87
	v_fmac_f32_e32 v96, v84, v84
	v_fmac_f32_e32 v97, v86, v86
	v_add_f32_e32 v96, v96, v97
	v_add_f32_e32 v95, v96, v95
	s_nop 1
	v_add_f32_dpp v240, v95, v95 quad_perm:[1,0,3,2] row_mask:0xf bank_mask:0xf
	s_nop 1
	v_add_f32_dpp v240, v240, v240 quad_perm:[2,3,0,1] row_mask:0xf bank_mask:0xf
	s_nop 1
	v_add_f32_dpp v240, v240, v240 row_half_mirror row_mask:0xf bank_mask:0xf
	s_nop 1
	v_add_f32_dpp v240, v240, v240 row_mirror row_mask:0xf bank_mask:0xf
	s_nop 1
	v_add_f32_dpp v240, v240, v240 row_bcast:15 row_mask:0xa bank_mask:0xf
	s_nop 1
	v_add_f32_dpp v240, v240, v240 row_bcast:31 row_mask:0xc bank_mask:0xf
	s_nop 0
	v_readlane_b32 s98, v240, 63
	s_nop 1
	s_and_b64 vcc, exec, s[0:1]
	s_waitcnt lgkmcnt(0)
	s_waitcnt lgkmcnt(0)
	s_waitcnt lgkmcnt(0)
	s_waitcnt lgkmcnt(0)
	s_waitcnt lgkmcnt(0)
	s_cbranch_vccnz .LBB0_1459
	s_waitcnt lgkmcnt(0)
	v_mov_b32_e32 v95, s98
	v_fmamk_f32 v95, v95, 0x3a800000, v94
	v_rsq_f32_e32 v128, v95
	s_ashr_i32 s3, s2, 31
	v_lshlrev_b32_e32 v116, 16, v46
	v_and_b32_e32 v117, 0xffff0000, v46
	v_lshlrev_b32_e32 v118, 16, v47
	v_and_b32_e32 v119, 0xffff0000, v47
	v_lshlrev_b32_e32 v120, 16, v42
	v_and_b32_e32 v121, 0xffff0000, v42
	v_lshlrev_b32_e32 v122, 16, v43
	v_and_b32_e32 v123, 0xffff0000, v43
	s_lshl_b64 s[18:19], s[2:3], 12
	v_pk_mul_f32 v[80:81], v[80:81], v[128:129] op_sel_hi:[1,0]
	v_pk_mul_f32 v[82:83], v[82:83], v[128:129] op_sel_hi:[1,0]
	v_pk_mul_f32 v[132:133], v[72:73], v[128:129] op_sel_hi:[1,0]
	v_pk_mul_f32 v[134:135], v[74:75], v[128:129] op_sel_hi:[1,0]
	v_lshlrev_b32_e32 v96, 16, v48
	v_and_b32_e32 v97, 0xffff0000, v48
	v_lshlrev_b32_e32 v114, 16, v49
	v_and_b32_e32 v115, 0xffff0000, v49
	v_lshlrev_b32_e32 v124, 16, v44
	v_and_b32_e32 v125, 0xffff0000, v44
	v_lshlrev_b32_e32 v126, 16, v45
	v_and_b32_e32 v127, 0xffff0000, v45
	v_lshl_add_u64 v[130:131], v[40:41], 0, s[18:19]
	v_pk_mul_f32 v[84:85], v[84:85], v[128:129] op_sel_hi:[1,0]
	v_pk_mul_f32 v[86:87], v[86:87], v[128:129] op_sel_hi:[1,0]
	v_pk_mul_f32 v[136:137], v[76:77], v[128:129] op_sel_hi:[1,0]
	v_pk_mul_f32 v[128:129], v[78:79], v[128:129] op_sel_hi:[1,0]
	s_nop 0
	v_pk_fma_f32 v[74:75], v[86:87], v[100:101], v[114:115]
	s_nop 0
	v_pk_fma_f32 v[78:79], v[82:83], v[104:105], v[118:119]
	v_pk_fma_f32 v[76:77], v[80:81], v[102:103], v[116:117]
	s_nop 0
	v_pk_fma_f32 v[82:83], v[134:135], v[108:109], v[122:123]
	v_pk_fma_f32 v[80:81], v[132:133], v[106:107], v[120:121]
	v_pk_fma_f32 v[72:73], v[84:85], v[98:99], v[96:97]
	s_nop 0
	v_pk_fma_f32 v[86:87], v[128:129], v[112:113], v[126:127]
	v_pk_fma_f32 v[84:85], v[136:137], v[110:111], v[124:125]
	global_store_dwordx4 v[130:131], v[80:83], off
	global_store_dwordx4 v[130:131], v[84:87], off offset:1024
	global_store_dwordx4 v[130:131], v[76:79], off offset:2048
	global_store_dwordx4 v[130:131], v[72:75], off offset:3072

.LBB0_1461:
	s_andn2_b64 vcc, exec, s[16:17]
	s_cbranch_vccnz .LBB0_1452
	v_and_b32_e32 v73, 0xffff0000, v16
	v_and_b32_e32 v75, 0xffff0000, v17
	v_lshlrev_b32_e32 v72, 16, v16
	v_lshlrev_b32_e32 v74, 16, v17
	v_mul_f32_e32 v76, v73, v73
	v_mul_f32_e32 v77, v75, v75
	v_fmac_f32_e32 v76, v72, v72
	v_fmac_f32_e32 v77, v74, v74
	v_add_f32_e32 v80, v76, v77
	v_and_b32_e32 v77, 0xffff0000, v58
	v_and_b32_e32 v79, 0xffff0000, v59
	v_lshlrev_b32_e32 v76, 16, v58
	v_lshlrev_b32_e32 v78, 16, v59
	v_mul_f32_e32 v81, v77, v77
	v_mul_f32_e32 v82, v79, v79
	v_fmac_f32_e32 v81, v76, v76
	v_fmac_f32_e32 v82, v78, v78
	v_add_f32_e32 v81, v81, v82
	v_add_f32_e32 v84, v81, v80
	v_and_b32_e32 v81, 0xffff0000, v60
	v_and_b32_e32 v83, 0xffff0000, v61
	v_lshlrev_b32_e32 v80, 16, v60
	v_lshlrev_b32_e32 v82, 16, v61
	v_mul_f32_e32 v85, v81, v81
	v_mul_f32_e32 v86, v83, v83
	v_fmac_f32_e32 v85, v80, v80
	v_fmac_f32_e32 v86, v82, v82
	v_add_f32_e32 v85, v85, v86
	v_add_f32_e32 v95, v85, v84
	v_and_b32_e32 v85, 0xffff0000, v62
	v_and_b32_e32 v87, 0xffff0000, v63
	v_lshlrev_b32_e32 v84, 16, v62
	v_lshlrev_b32_e32 v86, 16, v63
	s_waitcnt lgkmcnt(0)
	v_mul_f32_e32 v96, v85, v85
	v_mul_f32_e32 v97, v87, v87
	v_fmac_f32_e32 v96, v84, v84
	v_fmac_f32_e32 v97, v86, v86
	v_add_f32_e32 v96, v96, v97
	v_add_f32_e32 v95, v96, v95
	s_nop 1
	v_add_f32_dpp v240, v95, v95 quad_perm:[1,0,3,2] row_mask:0xf bank_mask:0xf
	s_nop 1
	v_add_f32_dpp v240, v240, v240 quad_perm:[2,3,0,1] row_mask:0xf bank_mask:0xf
	s_nop 1
	v_add_f32_dpp v240, v240, v240 row_half_mirror row_mask:0xf bank_mask:0xf
	s_nop 1
	v_add_f32_dpp v240, v240, v240 row_mirror row_mask:0xf bank_mask:0xf
	s_nop 1
	v_add_f32_dpp v240, v240, v240 row_bcast:15 row_mask:0xa bank_mask:0xf
	s_nop 1
	v_add_f32_dpp v240, v240, v240 row_bcast:31 row_mask:0xc bank_mask:0xf
	s_nop 0
	v_readlane_b32 s98, v240, 63
	s_nop 1
	s_and_b64 vcc, exec, s[0:1]
	s_waitcnt lgkmcnt(0)
	s_waitcnt lgkmcnt(0)
	s_waitcnt lgkmcnt(0)
	s_waitcnt lgkmcnt(0)
	s_waitcnt lgkmcnt(0)
	s_cbranch_vccnz .LBB0_1464
	s_waitcnt lgkmcnt(0)
	v_mov_b32_e32 v95, s98
	v_fmamk_f32 v95, v95, 0x3a800000, v94
	v_rsq_f32_e32 v128, v95
	s_ashr_i32 s9, s8, 31
	v_lshlrev_b32_e32 v116, 16, v4
	v_and_b32_e32 v117, 0xffff0000, v4
	v_lshlrev_b32_e32 v118, 16, v5
	v_and_b32_e32 v119, 0xffff0000, v5
	v_lshlrev_b32_e32 v120, 16, v0
	v_and_b32_e32 v121, 0xffff0000, v0
	v_lshlrev_b32_e32 v122, 16, v1
	v_and_b32_e32 v123, 0xffff0000, v1
	s_lshl_b64 s[16:17], s[8:9], 12
	v_pk_mul_f32 v[80:81], v[80:81], v[128:129] op_sel_hi:[1,0]
	v_pk_mul_f32 v[82:83], v[82:83], v[128:129] op_sel_hi:[1,0]
	v_pk_mul_f32 v[132:133], v[72:73], v[128:129] op_sel_hi:[1,0]
	v_pk_mul_f32 v[134:135], v[74:75], v[128:129] op_sel_hi:[1,0]
	v_lshlrev_b32_e32 v96, 16, v6
	v_and_b32_e32 v97, 0xffff0000, v6
	v_lshlrev_b32_e32 v114, 16, v7
	v_and_b32_e32 v115, 0xffff0000, v7
	v_lshlrev_b32_e32 v124, 16, v2
	v_and_b32_e32 v125, 0xffff0000, v2
	v_lshlrev_b32_e32 v126, 16, v3
	v_and_b32_e32 v127, 0xffff0000, v3
	v_lshl_add_u64 v[130:131], v[40:41], 0, s[16:17]
	v_pk_mul_f32 v[84:85], v[84:85], v[128:129] op_sel_hi:[1,0]
	v_pk_mul_f32 v[86:87], v[86:87], v[128:129] op_sel_hi:[1,0]
	v_pk_mul_f32 v[136:137], v[76:77], v[128:129] op_sel_hi:[1,0]
	v_pk_mul_f32 v[128:129], v[78:79], v[128:129] op_sel_hi:[1,0]
	s_nop 0
	v_pk_fma_f32 v[74:75], v[86:87], v[100:101], v[114:115]
	s_nop 0
	v_pk_fma_f32 v[78:79], v[82:83], v[104:105], v[118:119]
	v_pk_fma_f32 v[76:77], v[80:81], v[102:103], v[116:117]
	s_nop 0
	v_pk_fma_f32 v[82:83], v[134:135], v[108:109], v[122:123]
	v_pk_fma_f32 v[80:81], v[132:133], v[106:107], v[120:121]
	v_pk_fma_f32 v[72:73], v[84:85], v[98:99], v[96:97]
	s_nop 0
	v_pk_fma_f32 v[86:87], v[128:129], v[112:113], v[126:127]
	v_pk_fma_f32 v[84:85], v[136:137], v[110:111], v[124:125]
	global_store_dwordx4 v[130:131], v[80:83], off
	global_store_dwordx4 v[130:131], v[84:87], off offset:1024
	global_store_dwordx4 v[130:131], v[76:79], off offset:2048
	global_store_dwordx4 v[130:131], v[72:75], off offset:3072
.LBB0_1464:
	s_nop 1
	v_and_b32_e32 v73, 0xffff0000, v64
	v_and_b32_e32 v75, 0xffff0000, v65
	v_lshlrev_b32_e32 v72, 16, v64
	v_lshlrev_b32_e32 v74, 16, v65
	v_mul_f32_e32 v76, v73, v73
	v_mul_f32_e32 v77, v75, v75
	v_fmac_f32_e32 v76, v72, v72
	v_fmac_f32_e32 v77, v74, v74
	v_add_f32_e32 v80, v76, v77
	v_and_b32_e32 v77, 0xffff0000, v66
	v_and_b32_e32 v79, 0xffff0000, v67
	v_lshlrev_b32_e32 v76, 16, v66
	v_lshlrev_b32_e32 v78, 16, v67
	v_mul_f32_e32 v81, v77, v77
	v_mul_f32_e32 v82, v79, v79
	v_fmac_f32_e32 v81, v76, v76
	v_fmac_f32_e32 v82, v78, v78
	v_add_f32_e32 v81, v81, v82
	v_add_f32_e32 v84, v81, v80
	v_and_b32_e32 v81, 0xffff0000, v68
	v_and_b32_e32 v83, 0xffff0000, v69
	v_lshlrev_b32_e32 v80, 16, v68
	v_lshlrev_b32_e32 v82, 16, v69
	v_mul_f32_e32 v85, v81, v81
	v_mul_f32_e32 v86, v83, v83
	v_fmac_f32_e32 v85, v80, v80
	v_fmac_f32_e32 v86, v82, v82
	v_add_f32_e32 v85, v85, v86
	v_add_f32_e32 v95, v85, v84
	v_and_b32_e32 v85, 0xffff0000, v70
	v_and_b32_e32 v87, 0xffff0000, v71
	v_lshlrev_b32_e32 v84, 16, v70
	v_lshlrev_b32_e32 v86, 16, v71
	s_waitcnt lgkmcnt(0)
	v_mul_f32_e32 v96, v85, v85
	v_mul_f32_e32 v97, v87, v87
	v_fmac_f32_e32 v96, v84, v84
	v_fmac_f32_e32 v97, v86, v86
	v_add_f32_e32 v96, v96, v97
	v_add_f32_e32 v95, v96, v95
	s_nop 1
	v_add_f32_dpp v240, v95, v95 quad_perm:[1,0,3,2] row_mask:0xf bank_mask:0xf
	s_nop 1
	v_add_f32_dpp v240, v240, v240 quad_perm:[2,3,0,1] row_mask:0xf bank_mask:0xf
	s_nop 1
	v_add_f32_dpp v240, v240, v240 row_half_mirror row_mask:0xf bank_mask:0xf
	s_nop 1
	v_add_f32_dpp v240, v240, v240 row_mirror row_mask:0xf bank_mask:0xf
	s_nop 1
	v_add_f32_dpp v240, v240, v240 row_bcast:15 row_mask:0xa bank_mask:0xf
	s_nop 1
	v_add_f32_dpp v240, v240, v240 row_bcast:31 row_mask:0xc bank_mask:0xf
	s_nop 0
	v_readlane_b32 s98, v240, 63
	s_nop 1
	s_and_b64 vcc, exec, s[0:1]
	s_waitcnt lgkmcnt(0)
	s_waitcnt lgkmcnt(0)
	s_waitcnt lgkmcnt(0)
	s_waitcnt lgkmcnt(0)
	s_waitcnt lgkmcnt(0)
	s_cbranch_vccnz .LBB0_1452
	s_waitcnt lgkmcnt(0)
	v_mov_b32_e32 v95, s98
	v_fmamk_f32 v95, v95, 0x3a800000, v94
	v_rsq_f32_e32 v128, v95
	s_ashr_i32 s7, s6, 31
	v_lshlrev_b32_e32 v116, 16, v12
	v_and_b32_e32 v117, 0xffff0000, v12
	v_lshlrev_b32_e32 v118, 16, v13
	v_and_b32_e32 v119, 0xffff0000, v13
	v_lshlrev_b32_e32 v120, 16, v8
	v_and_b32_e32 v121, 0xffff0000, v8
	v_lshlrev_b32_e32 v122, 16, v9
	v_and_b32_e32 v123, 0xffff0000, v9
	s_lshl_b64 s[0:1], s[6:7], 12
	v_pk_mul_f32 v[80:81], v[80:81], v[128:129] op_sel_hi:[1,0]
	v_pk_mul_f32 v[82:83], v[82:83], v[128:129] op_sel_hi:[1,0]
	v_pk_mul_f32 v[132:133], v[72:73], v[128:129] op_sel_hi:[1,0]
	v_pk_mul_f32 v[134:135], v[74:75], v[128:129] op_sel_hi:[1,0]
	v_lshlrev_b32_e32 v96, 16, v14
	v_and_b32_e32 v97, 0xffff0000, v14
	v_lshlrev_b32_e32 v114, 16, v15
	v_and_b32_e32 v115, 0xffff0000, v15
	v_lshlrev_b32_e32 v124, 16, v10
	v_and_b32_e32 v125, 0xffff0000, v10
	v_lshlrev_b32_e32 v126, 16, v11
	v_and_b32_e32 v127, 0xffff0000, v11
	v_lshl_add_u64 v[130:131], v[40:41], 0, s[0:1]
	v_pk_mul_f32 v[84:85], v[84:85], v[128:129] op_sel_hi:[1,0]
	v_pk_mul_f32 v[86:87], v[86:87], v[128:129] op_sel_hi:[1,0]
	v_pk_mul_f32 v[136:137], v[76:77], v[128:129] op_sel_hi:[1,0]
	v_pk_mul_f32 v[128:129], v[78:79], v[128:129] op_sel_hi:[1,0]
	s_nop 0
	v_pk_fma_f32 v[74:75], v[86:87], v[100:101], v[114:115]
	s_nop 0
	v_pk_fma_f32 v[78:79], v[82:83], v[104:105], v[118:119]
	v_pk_fma_f32 v[76:77], v[80:81], v[102:103], v[116:117]
	s_nop 0
	v_pk_fma_f32 v[82:83], v[134:135], v[108:109], v[122:123]
	v_pk_fma_f32 v[80:81], v[132:133], v[106:107], v[120:121]
	v_pk_fma_f32 v[72:73], v[84:85], v[98:99], v[96:97]
	s_nop 0
	v_pk_fma_f32 v[86:87], v[128:129], v[112:113], v[126:127]
	v_pk_fma_f32 v[84:85], v[136:137], v[110:111], v[124:125]
	global_store_dwordx4 v[130:131], v[80:83], off
	global_store_dwordx4 v[130:131], v[84:87], off offset:1024
	global_store_dwordx4 v[130:131], v[76:79], off offset:2048
	global_store_dwordx4 v[130:131], v[72:75], off offset:3072
	s_branch .LBB0_1452
